# grid barriers 2..25 hand-written: XCD-last block bumps TOP without return, all leaders poll TOP >= nx*(g+1) (no TOPGEN hop, no XGEN)
# baseline (speedup 1.0000x reference)
.LBB0_146:
	s_or_b64 exec, exec, s[4:5]
	s_cmp_lt_u32 s61, 2
	s_cbranch_scc1 .LBB0_200
	s_waitcnt vmcnt(0) lgkmcnt(0)
	s_barrier
	v_readfirstlane_b32 s2, v162
	s_lshl_b32 s3, s33, 8
	s_add_u32 s6, s84, s3
	s_addc_u32 s7, s85, 0
	s_cmp_lg_u32 s2, 0
	s_cbranch_scc1 .Lgb1_wait
	s_mov_b64 s[8:9], exec
	s_mov_b64 exec, 1
	v_mov_b32_e32 v0, 0x12000
	ds_read_b64 v[2:3], v0
	v_mov_b32_e32 v0, 0x1400
	v_mov_b32_e32 v1, 1
	global_atomic_add v4, v0, v1, s[6:7] sc0
	s_mov_b32 s13, 0
	s_waitcnt lgkmcnt(0)
	v_readfirstlane_b32 s10, v2
	v_readfirstlane_b32 s11, v3
	v_mov_b32_e32 v0, 0x3400
	s_nop 3
	s_mul_i32 s10, s10, 2
	s_mul_i32 s11, s11, 2
	s_waitcnt vmcnt(0)
	v_readfirstlane_b32 s12, v4
	s_nop 3
	s_add_u32 s12, s12, 1
	s_cmp_lg_u32 s12, s10
	s_cbranch_scc1 .Lgb1_poll
	buffer_wbl2 sc1
	s_waitcnt vmcnt(0)
	global_atomic_add v0, v1, s[84:85]
.Lgb1_poll:
	global_load_dword v4, v0, s[84:85] sc1
	s_add_u32 s13, s13, 1
	s_waitcnt vmcnt(0)
	v_readfirstlane_b32 s12, v4
	s_nop 3
	s_cmp_gt_u32 s13, 0x80000
	s_cbranch_scc1 .Lgb1_done
	s_cmp_ge_u32 s12, s11
	s_cbranch_scc1 .Lgb1_done
	s_sleep 1
	s_branch .Lgb1_poll
.Lgb1_done:
	buffer_inv sc1
	s_waitcnt vmcnt(0)
	s_mov_b64 exec, s[8:9]
.Lgb1_wait:
	s_barrier
.LBB0_200:
	s_cmp_gt_i32 s60, 2
	s_waitcnt lgkmcnt(0)
	s_cselect_b64 s[2:3], -1, 0
	s_cmp_lt_i32 s61, 2
	s_cselect_b64 s[4:5], -1, 0
	s_or_b64 s[2:3], s[2:3], s[4:5]
	s_and_b64 vcc, exec, s[2:3]
	s_cbranch_vccnz .LBB0_472
	s_mov_b64 s[14:15], s[0:1]
	s_cmpk_gt_i32 s58, 0xc3f
	s_cbranch_scc1 .LBB0_418
	s_load_dwordx2 s[16:17], s[14:15], 0xe0
	s_load_dword s3, s[0:1], 0xf0
	v_lshrrev_b32_e32 v9, 3, v162
	v_lshlrev_b32_e32 v0, 3, v162
	v_and_b32_e32 v0, 56, v0
	s_waitcnt lgkmcnt(0)
	s_add_u32 s18, s16, 0x8b7a100
	s_addc_u32 s19, s17, 0
	v_mov_b32_e32 v99, 0
	v_lshlrev_b32_e32 v98, 11, v9
	v_lshl_add_u64 v[4:5], s[18:19], 0, v[98:99]
	v_lshlrev_b32_e32 v6, 1, v0
	v_mov_b32_e32 v7, v99
	v_xor_b32_e32 v10, v163, v162
	v_lshl_add_u64 v[100:101], v[4:5], 0, v[6:7]
	v_lshl_add_u64 v[4:5], s[16:17], 0, v[98:99]
	v_lshl_add_u64 v[102:103], v[4:5], 0, v[6:7]
	v_lshlrev_b32_e32 v5, 4, v10
	v_and_b32_e32 v96, 15, v162
	v_bfe_u32 v4, v162, 1, 3
	v_and_b32_e32 v5, 0x70, v5
	v_bfe_u32 v1, v162, 6, 1
	v_lshrrev_b32_e32 v3, 7, v162
	v_bitop3_b32 v4, v163, v4, 3 bitop3:0x6c
	v_lshl_or_b32 v160, v9, 7, v5
	v_lshlrev_b32_e32 v5, 7, v96
	v_lshl_or_b32 v6, v3, 13, v5
	v_lshl_or_b32 v5, v1, 13, v5
	v_lshlrev_b32_e32 v4, 4, v4
	v_or_b32_e32 v161, v6, v4
	v_or_b32_e32 v165, v5, v4
	v_xor_b32_e32 v4, 64, v4
	v_or_b32_e32 v166, v6, v4
	v_or_b32_e32 v167, v5, v4
	v_lshlrev_b32_e32 v4, 2, v96
	v_mov_b32_e32 v5, v99
	v_lshl_add_u64 v[4:5], s[16:17], 0, v[4:5]
	s_mov_b64 s[6:7], 0x1237a100
	v_lshl_add_u64 v[104:105], v[4:5], 0, s[6:7]
	s_mov_b64 s[6:7], 0x1237a140
	v_lshl_add_u64 v[106:107], v[4:5], 0, s[6:7]
	v_lshlrev_b32_e32 v4, 7, v1
	v_mov_b32_e32 v5, v99
	v_lshl_add_u64 v[4:5], s[16:17], 0, v[4:5]
	s_mov_b64 s[6:7], 0xdb7a100
	s_add_u32 s22, s16, 0xef7a100
	v_lshl_add_u64 v[108:109], v[4:5], 0, s[6:7]
	s_mov_b64 s[6:7], 0xe37a100
	v_lshlrev_b32_e32 v169, 6, v1
	v_cmp_eq_u32_e64 s[4:5], 0, v1
	s_addc_u32 s23, s17, 0
	v_lshl_add_u64 v[110:111], v[4:5], 0, s[6:7]
	v_lshlrev_b32_e32 v4, 1, v96
	v_mov_b32_e32 v5, v99
	v_and_b32_e32 v1, 7, v162
	s_add_u32 s24, s16, 0x6b00000
	v_lshl_add_u64 v[4:5], s[16:17], 0, v[4:5]
	s_mov_b64 s[6:7], 0x9b7a100
	v_lshl_or_b32 v98, v1, 4, v98
	s_addc_u32 s25, s17, 0
	v_lshl_add_u64 v[112:113], v[4:5], 0, s[6:7]
	v_lshl_add_u64 v[4:5], s[16:17], 0, v[98:99]
	s_mov_b64 s[6:7], 0x200
	v_bfe_u32 v8, v162, 4, 2
	v_lshlrev_b32_e32 v2, 10, v9
	v_lshlrev_b32_e32 v3, 6, v3
	s_add_u32 s26, s16, 0xcb7a100
	v_lshl_add_u64 v[114:115], v[4:5], 0, s[6:7]
	s_mov_b64 s[6:7], 0x8b7a300
	v_lshl_or_b32 v168, v8, 2, v3
	s_mov_b32 s21, 0
	v_or_b32_e32 v170, v169, v96
	s_addc_u32 s27, s17, 0
	s_lshl_b32 s66, s58, 1
	s_lshl_b32 s67, s3, 1
	v_lshl_add_u64 v[116:117], v[4:5], 0, s[6:7]
	s_lshl_b32 s68, s58, 7
	s_lshl_b32 s69, s3, 7
	s_mov_b64 s[8:9], 0
	s_movk_i32 s70, 0xff80
	s_mov_b32 s71, 0x10000
	s_mov_b64 s[28:29], 0x100
	s_mov_b64 s[30:31], 0x10000
	s_mov_b64 s[34:35], 0x10100
	s_mov_b64 s[36:37], 0x20000
	s_mov_b64 s[38:39], 0x20100
	s_mov_b64 s[40:41], 0x30000
	s_mov_b64 s[42:43], 0x30100
	v_lshlrev_b32_e32 v118, 1, v2
	v_mov_b32_e32 v119, v99
	v_lshlrev_b32_e32 v120, 1, v0
	v_mov_b32_e32 v121, v99
	s_mov_b64 s[44:45], 0x780
	s_mov_b32 s72, 0x3fff80
	s_mov_b32 s73, 0xf77a000
	s_mov_b32 s74, 0xf786000
	s_mov_b64 s[46:47], 0xf79e500
	s_movk_i32 s75, 0xf400
	s_movk_i32 s76, 0x7e00
	s_mov_b64 s[48:49], 0x2000000
	s_movk_i32 s77, 0xf0
	s_movk_i32 s78, 0xc0
	s_movk_i32 s79, 0x600
	s_movk_i32 s80, 0x200
	s_movk_i32 s81, 0x3d0
	s_movk_i32 s82, 0x3e0
	s_movk_i32 s83, 0x3f0
	s_movk_i32 s59, 0x3c0
	s_mov_b32 s86, 0xab89000
	s_mov_b32 s87, 0xab8a000
	s_mov_b32 s88, 0xab8b000
	s_mov_b32 s89, 0xab8c000
	s_mov_b32 s90, 0xab99000
	s_mov_b32 s91, 0xab9a000
	s_mov_b32 s92, 0xab9b000
	s_mov_b32 s93, 0xab9c000
	s_mov_b32 s94, 0xaba9000
	s_mov_b32 s95, 0xabaa000
	s_mov_b32 s96, 0xabab000
	s_mov_b32 s97, 0xabac000
	s_mov_b64 s[50:51], 0x60
	s_mov_b32 s2, s58
	v_and_b32_e32 v240, 63, v162
	v_lshrrev_b32_e32 v247, 6, v162
	v_lshrrev_b32_e32 v242, 3, v240
	v_lshl_add_u32 v242, v247, 5, v242
	v_and_b32_e32 v243, 7, v240
	v_lshrrev_b32_e32 v244, 4, v240
	v_xor_b32_e32 v243, v243, v244
	v_lshlrev_b32_e32 v243, 4, v243
	v_mov_b32_e32 v241, 0x800
	v_mad_u32_u24 v248, v242, v241, v243
	v_xor_b32_e32 v249, 64, v248
	v_add_u32_e32 v249, 0x4000, v249
	v_add_u32_e32 v250, 0x8000, v248
	v_xor_b32_e32 v251, 64, v248
	v_add_u32_e32 v251, 0xc000, v251
	v_and_b32_e32 v241, 15, v240
	v_lshrrev_b32_e32 v242, 1, v241
	v_xor_b32_e32 v242, v242, v244
	v_lshlrev_b32_e32 v242, 4, v242
	v_lshl_or_b32 v242, v241, 7, v242
	v_lshrrev_b32_e32 v243, 1, v247
	v_lshl_or_b32 v252, v243, 13, v242
	v_xor_b32_e32 v253, 64, v252
	v_and_b32_e32 v243, 1, v247
	v_lshl_or_b32 v254, v243, 13, v242
	v_xor_b32_e32 v255, 64, v254
	s_load_dwordx2 s[6:7], s[0:1], 0xe0
	s_load_dword s20, s[0:1], 0xf0
	v_and_b32_e32 v155, 63, v162
	v_lshrrev_b32_e32 v154, 6, v162
	v_and_b32_e32 v152, 15, v155
	v_lshrrev_b32_e32 v153, 4, v155
	v_lshlrev_b32_e32 v153, 4, v153
	v_lshl_add_u32 v153, v154, 9, v153
	v_lshl_add_u32 v152, v152, 11, v153
	s_waitcnt lgkmcnt(0)
	s_mov_b32 s32, s58

.LBB0_418:
	s_cmp_lt_i32 s61, 3
	s_cbranch_scc1 .LBB0_472
	s_waitcnt vmcnt(0) lgkmcnt(0)
	s_barrier
	v_readfirstlane_b32 s2, v162
	s_lshl_b32 s3, s33, 8
	s_add_u32 s6, s84, s3
	s_addc_u32 s7, s85, 0
	s_cmp_lg_u32 s2, 0
	s_cbranch_scc1 .Lgb2_wait
	s_mov_b64 s[8:9], exec
	s_mov_b64 exec, 1
	v_mov_b32_e32 v0, 0x12000
	ds_read_b64 v[2:3], v0
	v_mov_b32_e32 v0, 0x1400
	v_mov_b32_e32 v1, 1
	global_atomic_add v4, v0, v1, s[6:7] sc0
	s_mov_b32 s13, 0
	s_waitcnt lgkmcnt(0)
	v_readfirstlane_b32 s10, v2
	v_readfirstlane_b32 s11, v3
	v_mov_b32_e32 v0, 0x3400
	s_nop 3
	s_mul_i32 s10, s10, 3
	s_mul_i32 s11, s11, 3
	s_waitcnt vmcnt(0)
	v_readfirstlane_b32 s12, v4
	s_nop 3
	s_add_u32 s12, s12, 1
	s_cmp_lg_u32 s12, s10
	s_cbranch_scc1 .Lgb2_poll
	buffer_wbl2 sc1
	s_waitcnt vmcnt(0)
	global_atomic_add v0, v1, s[84:85]

.Lgb2_wait:
	s_barrier
.LBB0_472:
	s_cmp_gt_i32 s60, 3
	s_cselect_b64 s[2:3], -1, 0
	s_cmp_lt_i32 s61, 3
	s_cselect_b64 s[4:5], -1, 0
	s_or_b64 s[2:3], s[2:3], s[4:5]
	s_and_b64 vcc, exec, s[2:3]
	v_lshl_add_u32 v128, s58, 8, v162
	s_cbranch_vccnz .LBB0_545
	s_mov_b64 s[16:17], s[0:1]
	s_load_dword s2, s[0:1], 0xf0
	s_load_dwordx2 s[14:15], s[16:17], 0xe0
	v_lshl_add_u32 v8, s58, 8, v162
	s_add_u32 s6, s0, 0xf0
	s_mov_b32 s3, 0x200000
	s_addc_u32 s7, s1, 0
	s_waitcnt lgkmcnt(0)
	s_lshl_b32 s12, s2, 8
	v_cmp_gt_i32_e32 vcc, s3, v8
	s_and_saveexec_b64 s[18:19], vcc
	s_cbranch_execz .LBB0_486
	s_load_dwordx4 s[48:51], s[0:1], 0x68
	s_load_dword s64, s[0:1], 0xf0
	v_lshlrev_b32_e32 v26, 4, v162
	v_lshlrev_b32_e32 v27, 5, v162
	s_waitcnt lgkmcnt(0)
	global_load_dwordx4 v[28:31], v27, s[48:49]
	global_load_dwordx4 v[32:35], v27, s[48:49] offset:16
	s_add_u32 s48, s48, 0x2000
	s_addc_u32 s49, s49, 0
	global_load_dwordx4 v[36:39], v27, s[48:49]
	global_load_dwordx4 v[40:43], v27, s[48:49] offset:16
	s_add_u32 s48, s48, 0x2000
	s_addc_u32 s49, s49, 0
	global_load_dwordx4 v[44:47], v27, s[48:49]
	global_load_dwordx4 v[48:51], v27, s[48:49] offset:16
	s_add_u32 s48, s48, 0x2000
	s_addc_u32 s49, s49, 0
	global_load_dwordx4 v[52:55], v27, s[48:49]
	global_load_dwordx4 v[56:59], v27, s[48:49] offset:16
	s_add_u32 s48, s48, 0x2000
	s_addc_u32 s49, s49, 0
	global_load_dwordx4 v[60:63], v27, s[48:49]
	global_load_dwordx4 v[64:67], v27, s[48:49] offset:16
	global_load_dwordx4 v[68:71], v27, s[50:51]
	global_load_dwordx4 v[72:75], v27, s[50:51] offset:16
	s_mov_b32 s3, s58

.LBB0_491:
	s_or_b64 exec, exec, s[4:5]
	s_cmp_lt_i32 s61, 4
	s_cbranch_scc1 .LBB0_545
	s_waitcnt vmcnt(0) lgkmcnt(0)
	s_barrier
	v_readfirstlane_b32 s2, v162
	s_lshl_b32 s3, s33, 8
	s_add_u32 s6, s84, s3
	s_addc_u32 s7, s85, 0
	s_cmp_lg_u32 s2, 0
	s_cbranch_scc1 .Lgb3_wait
	s_mov_b64 s[8:9], exec
	s_mov_b64 exec, 1
	v_mov_b32_e32 v0, 0x12000
	ds_read_b64 v[2:3], v0
	v_mov_b32_e32 v0, 0x1400
	v_mov_b32_e32 v1, 1
	global_atomic_add v4, v0, v1, s[6:7] sc0
	s_mov_b32 s13, 0
	s_waitcnt lgkmcnt(0)
	v_readfirstlane_b32 s10, v2
	v_readfirstlane_b32 s11, v3
	v_mov_b32_e32 v0, 0x3400
	s_nop 3
	s_mul_i32 s10, s10, 4
	s_mul_i32 s11, s11, 4
	s_waitcnt vmcnt(0)
	v_readfirstlane_b32 s12, v4
	s_nop 3
	s_add_u32 s12, s12, 1
	s_cmp_lg_u32 s12, s10
	s_cbranch_scc1 .Lgb3_poll
	buffer_wbl2 sc1
	s_waitcnt vmcnt(0)
	global_atomic_add v0, v1, s[84:85]

.Lgb3_wait:
	s_barrier
.LBB0_545:
	s_cmp_gt_i32 s60, 4
	s_cselect_b64 s[2:3], -1, 0
	s_cmp_lt_i32 s61, 4
	s_cselect_b64 s[4:5], -1, 0
	s_or_b64 s[2:3], s[2:3], s[4:5]
	s_and_b64 vcc, exec, s[2:3]
	v_bfe_u32 v169, v162, 2, 2
	v_not_b32_e32 v166, v162
	v_lshrrev_b32_e32 v165, 6, v162
	v_cmp_gt_u32_e64 s[4:5], 64, v162
	v_and_b32_e32 v168, 48, v162
	s_cbranch_vccnz .LBB0_775
	v_lshlrev_b32_e32 v7, 3, v162
	v_bfe_u32 v65, v162, 4, 2
	v_and_b32_e32 v64, 0x78, v7
	v_mov_b32_e32 v9, 0x11500
	s_mov_b64 s[62:63], s[0:1]
	v_lshlrev_b32_e32 v0, 1, v64
	v_lshl_or_b32 v111, v65, 5, v9
	v_mul_u32_u24_e32 v9, 0x88, v163
	s_load_dwordx2 s[64:65], s[62:63], 0xe0
	v_lshl_add_u32 v112, v9, 1, v0
	v_add_u32_e32 v9, 0x100, v162
	v_lshrrev_b32_e32 v114, 4, v9
	v_mul_u32_u24_e32 v10, 0x88, v114
	v_lshl_add_u32 v115, v10, 1, v0
	v_add_u32_e32 v10, 0x200, v162
	v_lshrrev_b32_e32 v117, 4, v10
	v_and_b32_e32 v1, 63, v162
	v_and_b32_e32 v68, 15, v162
	s_waitcnt lgkmcnt(0)
	s_add_u32 s66, s64, 0x1457d700
	v_lshlrev_b32_e32 v2, 4, v165
	v_mul_u32_u24_e32 v10, 0x88, v117
	s_addc_u32 s67, s65, 0
	v_lshl_or_b32 v67, v65, 2, v2
	v_lshlrev_b32_e32 v133, 2, v1
	v_lshl_add_u32 v118, v10, 1, v0
	v_add_u32_e32 v10, 0x300, v162
	v_cmp_eq_u32_e64 s[6:7], 0, v1
	v_cmp_gt_u32_e64 s[8:9], 2, v1
	v_cmp_gt_u32_e64 s[10:11], 4, v1
	v_cmp_gt_u32_e64 s[12:13], 8, v1
	v_cmp_gt_u32_e64 s[14:15], 16, v1
	v_cmp_gt_u32_e64 s[16:17], 32, v1
	v_mul_u32_u24_e32 v1, 0x88, v68
	v_mov_b32_e32 v73, 0
	v_or_b32_e32 v4, 16, v68
	v_or_b32_e32 v5, 32, v68
	v_or_b32_e32 v6, 48, v68
	v_lshrrev_b32_e32 v120, 4, v10
	v_lshl_add_u32 v124, v1, 1, v168
	v_mov_b32_e32 v1, 0x11400
	v_or_b32_e32 v14, 1, v67
	v_or_b32_e32 v15, 2, v67
	v_or_b32_e32 v16, 3, v67
	s_add_u32 s70, s64, 0x1037a100
	v_and_b32_e32 v66, 56, v7
	v_and_b32_e32 v109, 24, v7
	v_lshl_or_b32 v7, v65, 3, v169
	v_mul_u32_u24_e32 v10, 0x88, v120
	v_lshl_or_b32 v125, v68, 2, v1
	v_lshl_or_b32 v126, v4, 2, v1
	v_lshl_or_b32 v127, v5, 2, v1
	v_lshl_or_b32 v130, v6, 2, v1
	v_lshl_or_b32 v132, v67, 2, v1
	v_lshl_or_b32 v135, v14, 2, v1
	v_lshl_or_b32 v137, v15, 2, v1
	v_lshl_or_b32 v139, v16, 2, v1
	s_addc_u32 s71, s65, 0
	v_mov_b32_e32 v1, v73
	v_lshlrev_b32_e32 v3, 7, v67
	v_lshlrev_b32_e32 v8, 1, v68
	v_lshlrev_b32_e32 v129, 5, v165
	v_lshl_add_u32 v121, v10, 1, v0
	v_lshrrev_b32_e32 v147, 3, v162
	v_lshrrev_b32_e32 v123, 3, v9
	v_mul_u32_u24_e32 v131, 0x90, v7
	v_mul_u32_u24_e32 v11, 0x110, v7
	v_or_b32_e32 v7, 32, v7
	v_or_b32_e32 v2, v2, v68
	v_mul_u32_u24_e32 v17, 0x90, v67
	v_lshl_add_u64 v[96:97], s[70:71], 0, v[0:1]
	v_mbcnt_lo_u32_b32 v0, -1, 0
	s_mov_b64 s[54:55], src_shared_base
	v_or_b32_e32 v70, v3, v68
	v_lshlrev_b32_e32 v72, 1, v66
	v_or_b32_e32 v110, v109, v129
	v_mul_u32_u24_e32 v10, 0x90, v147
	v_mul_u32_u24_e32 v9, 0x90, v123
	v_mul_u32_u24_e32 v7, 0x90, v7
	v_mul_u32_u24_e32 v12, 0x110, v2
	v_mul_u32_u24_e32 v2, 0x90, v2
	v_mul_u32_u24_e32 v13, 0x110, v67
	v_or_b32_e32 v134, v17, v8
	s_add_u32 s2, s64, 0x1247a100
	v_mbcnt_hi_u32_b32 v157, -1, v0
	v_bfrev_b32_e32 v0, 0.5
	v_mov_b32_e32 v71, v73
	v_or_b32_e32 v69, 0x11400, v133
	v_or_b32_e32 v108, 0x11500, v133
	v_add_u32_e32 v113, 0x4400, v112
	v_add_u32_e32 v116, 0x4400, v115
	v_add_u32_e32 v119, 0x4400, v118
	v_add_u32_e32 v122, 0x4400, v121
	s_mov_b32 s69, 0
	v_cmp_le_u32_e64 s[18:19], v68, v67
	v_cmp_le_u32_e64 s[20:21], v4, v67
	v_cmp_le_u32_e64 s[22:23], v5, v67
	v_cmp_le_u32_e64 s[24:25], v6, v67
	v_cmp_le_u32_e64 s[26:27], v68, v14
	v_add_u32_e32 v136, 0x90, v134
	v_cmp_le_u32_e64 s[28:29], v4, v14
	v_cmp_le_u32_e64 s[30:31], v5, v14
	v_cmp_le_u32_e64 s[34:35], v6, v14
	v_cmp_le_u32_e64 s[36:37], v68, v15
	v_add_u32_e32 v138, 0x120, v134
	v_cmp_le_u32_e64 s[38:39], v4, v15
	v_cmp_le_u32_e64 s[40:41], v5, v15
	v_cmp_le_u32_e64 s[42:43], v6, v15
	v_cmp_le_u32_e64 s[44:45], v68, v16
	v_add_u32_e32 v140, 0x1b0, v134
	v_cmp_le_u32_e64 s[46:47], v4, v16
	v_cmp_le_u32_e64 s[48:49], v5, v16
	v_cmp_le_u32_e64 s[50:51], v6, v16
	v_lshl_or_b32 v74, v14, 7, v68
	v_mov_b32_e32 v75, v73
	v_lshl_or_b32 v76, v15, 7, v68
	v_mov_b32_e32 v77, v73
	v_lshl_or_b32 v78, v16, 7, v68
	v_mov_b32_e32 v79, v73
	s_addc_u32 s3, s65, 0
	v_lshl_add_u64 v[80:81], s[70:71], 0, v[72:73]
	v_or_b32_e32 v82, v3, v4
	v_mov_b32_e32 v83, v73
	s_waitcnt vmcnt(2)
	v_or_b32_e32 v84, v3, v5
	v_mov_b32_e32 v85, v73
	v_or_b32_e32 v86, v3, v6
	v_mov_b32_e32 v87, v73
	s_waitcnt vmcnt(1)
	v_or_b32_e32 v88, 64, v70
	v_mov_b32_e32 v89, v73
	v_or_b32_e32 v90, 0x50, v70
	v_mov_b32_e32 v91, v73
	s_waitcnt vmcnt(0)
	v_or_b32_e32 v92, 0x60, v70
	v_mov_b32_e32 v93, v73
	v_or_b32_e32 v94, 0x70, v70
	v_mov_b32_e32 v95, v73
	v_sub_u32_e32 v141, 0, v67
	v_not_b32_e32 v142, v123
	v_not_b32_e32 v143, v147
	v_not_b32_e32 v144, v120
	v_not_b32_e32 v145, v117
	v_not_b32_e32 v146, v114
	v_not_b32_e32 v148, v163
	v_mov_b32_e32 v98, 0x11ff0
	v_mov_b32_e32 v101, s55
	v_mov_b32_e32 v100, 0x11ff0
	s_mov_b32 s59, 0xab7a100
	v_add_u32_e32 v149, v72, v10
	v_add_u32_e32 v150, v72, v9
	v_add_u32_e32 v151, v8, v13
	v_add_u32_e32 v152, v168, v12
	v_mov_b32_e32 v153, 0x114fc
	v_add_u32_e32 v154, v168, v2
	v_add_u32_e32 v155, v109, v11
	v_add_u32_e32 v156, v110, v7
	s_mov_b32 s74, 0x6000000
	v_lshlrev_b32_e32 v72, 1, v68
	v_lshl_or_b32 v158, v157, 2, v0
	s_branch .LBB0_549

.LBB0_721:
	s_cmp_lt_i32 s61, 5
	s_cbranch_scc1 .LBB0_775
	s_waitcnt vmcnt(0) lgkmcnt(0)
	s_barrier
	v_readfirstlane_b32 s2, v162
	s_lshl_b32 s3, s33, 8
	s_add_u32 s6, s84, s3
	s_addc_u32 s7, s85, 0
	s_cmp_lg_u32 s2, 0
	s_cbranch_scc1 .Lgb4_wait
	s_mov_b64 s[8:9], exec
	s_mov_b64 exec, 1
	v_mov_b32_e32 v0, 0x12000
	ds_read_b64 v[2:3], v0
	v_mov_b32_e32 v0, 0x1400
	v_mov_b32_e32 v1, 1
	global_atomic_add v4, v0, v1, s[6:7] sc0
	s_mov_b32 s13, 0
	s_waitcnt lgkmcnt(0)
	v_readfirstlane_b32 s10, v2
	v_readfirstlane_b32 s11, v3
	v_mov_b32_e32 v0, 0x3400
	s_nop 3
	s_mul_i32 s10, s10, 5
	s_mul_i32 s11, s11, 5
	s_waitcnt vmcnt(0)
	v_readfirstlane_b32 s12, v4
	s_nop 3
	s_add_u32 s12, s12, 1
	s_cmp_lg_u32 s12, s10
	s_cbranch_scc1 .Lgb4_poll
	buffer_wbl2 sc1
	s_waitcnt vmcnt(0)
	global_atomic_add v0, v1, s[84:85]

.Lgb4_wait:
	s_barrier
.LBB0_775:
	s_cmp_gt_i32 s60, 5
	s_cselect_b64 s[2:3], -1, 0
	s_cmp_lt_i32 s61, 5
	s_cselect_b64 s[4:5], -1, 0
	s_or_b64 s[2:3], s[2:3], s[4:5]
	s_and_b64 vcc, exec, s[2:3]
	v_lshrrev_b32_e32 v167, 5, v162
	s_cbranch_vccnz .LBB0_833
	v_and_b32_e32 v0, 30, v167
	v_lshl_add_u32 v8, s58, 3, v0
	s_movk_i32 s2, 0x2000
	s_mov_b64 s[10:11], s[0:1]
	v_cmp_gt_i32_e32 vcc, s2, v8
	s_and_saveexec_b64 s[8:9], vcc
	s_cbranch_execz .LBB0_779
	s_load_dwordx2 s[2:3], s[10:11], 0xe0
	s_load_dwordx4 s[4:7], s[10:11], 0x88
	s_load_dword s12, s[0:1], 0xf0
	v_lshlrev_b32_e32 v0, 3, v162
	v_and_b32_e32 v0, 0x1f8, v0
	v_mbcnt_lo_u32_b32 v1, -1, 0
	v_mbcnt_hi_u32_b32 v1, -1, v1
	v_or_b32_e32 v3, 0x200, v0
	v_lshrrev_b32_e32 v4, 1, v162
	v_and_b32_e32 v2, 64, v1
	v_and_b32_e32 v10, 28, v4
	v_mov_b32_e32 v11, 0
	v_lshrrev_b32_e32 v3, 4, v3
	v_add_u32_e32 v2, 64, v2
	s_waitcnt lgkmcnt(0)
	v_lshl_add_u64 v[12:13], s[4:5], 0, v[10:11]
	v_and_b32_e32 v10, 60, v3
	v_xor_b32_e32 v3, 32, v1
	v_cmp_lt_i32_e32 vcc, v3, v2
	v_lshl_add_u64 v[14:15], s[4:5], 0, v[10:11]
	v_lshlrev_b32_e32 v10, 2, v0
	v_cndmask_b32_e32 v3, v1, v3, vcc
	v_lshlrev_b32_e32 v23, 2, v3
	v_xor_b32_e32 v3, 16, v1
	v_cmp_lt_i32_e32 vcc, v3, v2
	v_and_b32_e32 v0, 63, v162
	v_ashrrev_i32_e32 v9, 31, v8
	v_cndmask_b32_e32 v3, v1, v3, vcc
	v_lshlrev_b32_e32 v27, 2, v3
	v_xor_b32_e32 v3, 8, v1
	v_cmp_lt_i32_e32 vcc, v3, v2
	s_lshl_b32 s10, s12, 3
	v_lshl_add_u64 v[16:17], s[6:7], 0, v[10:11]
	v_cndmask_b32_e32 v3, v1, v3, vcc
	v_lshlrev_b32_e32 v29, 2, v3
	v_xor_b32_e32 v3, 4, v1
	v_cmp_lt_i32_e32 vcc, v3, v2
	v_lshlrev_b32_e32 v10, 4, v0
	s_ashr_i32 s11, s10, 31
	v_cndmask_b32_e32 v3, v1, v3, vcc
	v_lshlrev_b32_e32 v36, 2, v3
	v_xor_b32_e32 v3, 2, v1
	v_cmp_lt_i32_e32 vcc, v3, v2
	s_lshl_b64 s[6:7], s[10:11], 12
	s_lshl_b64 s[12:13], s[10:11], 11
	v_cndmask_b32_e32 v3, v1, v3, vcc
	v_lshlrev_b32_e32 v37, 2, v3
	v_xor_b32_e32 v3, 1, v1
	v_cmp_lt_i32_e32 vcc, v3, v2
	s_mov_b64 s[14:15], 0
	s_mov_b32 s16, 0x3a800000
	v_cndmask_b32_e32 v1, v1, v3, vcc
	v_lshlrev_b32_e32 v38, 2, v1
	v_lshlrev_b64 v[0:1], 12, v[8:9]
	v_lshl_add_u64 v[18:19], s[2:3], 0, v[0:1]
	v_lshlrev_b64 v[0:1], 11, v[8:9]
	v_lshl_add_u64 v[20:21], s[2:3], 0, v[0:1]
	s_mov_b32 s2, 0x1037b000
	v_mov_b32_e32 v22, 0x358637bd
	s_mov_b32 s3, 0x800000
	s_mov_b32 s11, 0x1257a000
	s_mov_b32 s17, 0x1257b000
	s_movk_i32 s18, 0x1fff

.LBB0_779:
	s_or_b64 exec, exec, s[8:9]
	s_cmp_lt_u32 s61, 6
	s_cbranch_scc1 .LBB0_833
	s_waitcnt vmcnt(0) lgkmcnt(0)
	s_barrier
	v_readfirstlane_b32 s2, v162
	s_lshl_b32 s3, s33, 8
	s_add_u32 s6, s84, s3
	s_addc_u32 s7, s85, 0
	s_cmp_lg_u32 s2, 0
	s_cbranch_scc1 .Lgb5_wait
	s_mov_b64 s[8:9], exec
	s_mov_b64 exec, 1
	v_mov_b32_e32 v0, 0x12000
	ds_read_b64 v[2:3], v0
	v_mov_b32_e32 v0, 0x1400
	v_mov_b32_e32 v1, 1
	global_atomic_add v4, v0, v1, s[6:7] sc0
	s_mov_b32 s13, 0
	s_waitcnt lgkmcnt(0)
	v_readfirstlane_b32 s10, v2
	v_readfirstlane_b32 s11, v3
	v_mov_b32_e32 v0, 0x3400
	s_nop 3
	s_mul_i32 s10, s10, 6
	s_mul_i32 s11, s11, 6
	s_waitcnt vmcnt(0)
	v_readfirstlane_b32 s12, v4
	s_nop 3
	s_add_u32 s12, s12, 1
	s_cmp_lg_u32 s12, s10
	s_cbranch_scc1 .Lgb5_poll
	buffer_wbl2 sc1
	s_waitcnt vmcnt(0)
	global_atomic_add v0, v1, s[84:85]

.Lgb5_wait:
	s_barrier
.LBB0_833:
	s_cmp_gt_i32 s60, 6
	s_cselect_b64 s[2:3], -1, 0
	s_cmp_lt_i32 s61, 6
	s_cselect_b64 s[4:5], -1, 0
	s_or_b64 s[2:3], s[2:3], s[4:5]
	s_and_b64 vcc, exec, s[2:3]
	s_cbranch_vccnz .LBB0_893
	s_load_dwordx2 s[4:5], s[0:1], 0xe0
	s_load_dword s16, s[0:1], 0xf0
	v_and_b32_e32 v240, 63, v162
	v_lshrrev_b32_e32 v247, 6, v162
	v_lshrrev_b32_e32 v242, 3, v240
	v_lshl_add_u32 v242, v247, 5, v242
	v_and_b32_e32 v243, 7, v240
	v_lshrrev_b32_e32 v244, 4, v240
	v_xor_b32_e32 v243, v243, v244
	v_lshlrev_b32_e32 v243, 4, v243
	v_mov_b32_e32 v241, 0x1000
	v_mad_u32_u24 v248, v242, v241, v243
	v_xor_b32_e32 v249, 64, v248
	v_add_u32_e32 v249, 0x8000, v249
	v_add_u32_e32 v250, 0x10000, v248
	v_xor_b32_e32 v251, 64, v248
	v_add_u32_e32 v251, 0x18000, v251
	v_and_b32_e32 v241, 15, v240
	v_lshrrev_b32_e32 v242, 1, v241
	v_xor_b32_e32 v242, v242, v244
	v_lshlrev_b32_e32 v242, 4, v242
	v_lshl_or_b32 v242, v241, 7, v242
	v_lshrrev_b32_e32 v243, 1, v247
	v_lshl_or_b32 v252, v243, 13, v242
	v_xor_b32_e32 v253, 64, v252
	v_and_b32_e32 v243, 1, v247
	v_lshl_or_b32 v254, v243, 13, v242
	v_xor_b32_e32 v255, 64, v254
	v_and_b32_e32 v240, 63, v162
	v_and_b32_e32 v241, 15, v240
	v_lshrrev_b32_e32 v242, 4, v240
	v_lshrrev_b32_e32 v243, 1, v247
	v_and_b32_e32 v244, 1, v247
	v_lshl_or_b32 v245, v244, 6, v241
	v_lshlrev_b32_e32 v243, 4, v243
	v_add_u32_e32 v243, v243, v242
	v_lshl_add_u32 v246, v243, 12, v245
	v_lshlrev_b32_e32 v246, 2, v246
	v_lshlrev_b32_e32 v245, 2, v245
	s_waitcnt lgkmcnt(0)
	s_add_u32 s26, s4, 0x1257a100
	s_addc_u32 s27, s5, 0
	s_add_u32 s28, s4, 0x1880000
	s_addc_u32 s29, s5, 0
	s_mov_b32 s15, s58

.LBB0_897:
	s_or_b64 exec, exec, s[10:11]
	s_cmp_lt_u32 s61, 8
	s_cbranch_scc1 .LBB0_951
	s_waitcnt vmcnt(0) lgkmcnt(0)
	s_barrier
	v_readfirstlane_b32 s2, v162
	s_lshl_b32 s3, s33, 8
	s_add_u32 s6, s84, s3
	s_addc_u32 s7, s85, 0
	s_cmp_lg_u32 s2, 0
	s_cbranch_scc1 .Lgb7_wait
	s_mov_b64 s[8:9], exec
	s_mov_b64 exec, 1
	v_mov_b32_e32 v0, 0x12000
	ds_read_b64 v[2:3], v0
	v_mov_b32_e32 v0, 0x1400
	v_mov_b32_e32 v1, 1
	global_atomic_add v4, v0, v1, s[6:7] sc0
	s_mov_b32 s13, 0
	s_waitcnt lgkmcnt(0)
	v_readfirstlane_b32 s10, v2
	v_readfirstlane_b32 s11, v3
	v_mov_b32_e32 v0, 0x3400
	s_nop 3
	s_mul_i32 s10, s10, 7
	s_mul_i32 s11, s11, 7
	s_waitcnt vmcnt(0)
	v_readfirstlane_b32 s12, v4
	s_nop 3
	s_add_u32 s12, s12, 1
	s_cmp_lg_u32 s12, s10
	s_cbranch_scc1 .Lgb7_poll
	buffer_wbl2 sc1
	s_waitcnt vmcnt(0)
	global_atomic_add v0, v1, s[84:85]

.Lgb7_wait:
	s_barrier
.LBB0_951:
	s_cmp_gt_i32 s60, 8
	s_cselect_b64 s[2:3], -1, 0
	s_cmp_lt_i32 s61, 8
	s_cselect_b64 s[4:5], -1, 0
	s_or_b64 s[2:3], s[2:3], s[4:5]
	s_and_b64 vcc, exec, s[2:3]
	s_cbranch_vccnz .LBB0_1015
	s_load_dwordx2 s[4:5], s[0:1], 0xe0
	s_load_dword s16, s[0:1], 0xf0
	v_and_b32_e32 v240, 63, v162
	v_lshrrev_b32_e32 v247, 6, v162
	v_lshrrev_b32_e32 v242, 3, v240
	v_lshl_add_u32 v242, v247, 5, v242
	v_and_b32_e32 v243, 7, v240
	v_lshrrev_b32_e32 v244, 4, v240
	v_xor_b32_e32 v243, v243, v244
	v_lshlrev_b32_e32 v243, 4, v243
	v_mov_b32_e32 v241, 0x800
	v_mad_u32_u24 v248, v242, v241, v243
	v_xor_b32_e32 v249, 64, v248
	v_add_u32_e32 v249, 0x4000, v249
	v_add_u32_e32 v250, 0x8000, v248
	v_xor_b32_e32 v251, 64, v248
	v_add_u32_e32 v251, 0xc000, v251
	v_and_b32_e32 v241, 15, v240
	v_lshrrev_b32_e32 v242, 1, v241
	v_xor_b32_e32 v242, v242, v244
	v_lshlrev_b32_e32 v242, 4, v242
	v_lshl_or_b32 v242, v241, 7, v242
	v_lshrrev_b32_e32 v243, 1, v247
	v_lshl_or_b32 v252, v243, 13, v242
	v_xor_b32_e32 v253, 64, v252
	v_and_b32_e32 v243, 1, v247
	v_lshl_or_b32 v254, v243, 13, v242
	v_xor_b32_e32 v255, 64, v254
	v_and_b32_e32 v240, 63, v162
	v_and_b32_e32 v241, 15, v240
	v_lshrrev_b32_e32 v242, 4, v240
	v_mul_u32_u24_e32 v245, 0x1400, v247
	v_mul_u32_u24_e32 v243, 80, v241
	v_add_u32_e32 v243, v243, v245
	v_lshl_add_u32 v244, v242, 3, v243
	v_lshrrev_b32_e32 v243, 2, v240
	v_mul_u32_u24_e32 v246, 80, v243
	v_add_u32_e32 v246, v246, v245
	v_and_b32_e32 v241, 3, v240
	v_lshl_add_u32 v246, v241, 4, v246
	v_mov_b32_e32 v245, v244
	v_lshrrev_b32_e32 v242, 1, v247
	v_lshl_add_u32 v243, v242, 6, v243
	v_mov_b32_e32 v242, 0x1600
	v_mul_u32_u24_e32 v243, v243, v242
	v_and_b32_e32 v242, 1, v247
	v_lshl_add_u32 v243, v242, 6, v243
	v_lshl_add_u32 v239, v241, 4, v243
	s_waitcnt lgkmcnt(0)
	s_add_u32 s26, s4, 0x8b7a100
	s_addc_u32 s27, s5, 0
	s_add_u32 s28, s4, 0x2480000
	s_addc_u32 s29, s5, 0
	s_mov_b32 s15, s58

.Lf8_end:
.LBB0_961:
	s_cmp_lt_i32 s61, 9
	s_cbranch_scc1 .LBB0_1015
	s_waitcnt vmcnt(0) lgkmcnt(0)
	s_barrier
	v_readfirstlane_b32 s2, v162
	s_lshl_b32 s3, s33, 8
	s_add_u32 s6, s84, s3
	s_addc_u32 s7, s85, 0
	s_cmp_lg_u32 s2, 0
	s_cbranch_scc1 .Lgb8_wait
	s_mov_b64 s[8:9], exec
	s_mov_b64 exec, 1
	v_mov_b32_e32 v0, 0x12000
	ds_read_b64 v[2:3], v0
	v_mov_b32_e32 v0, 0x1400
	v_mov_b32_e32 v1, 1
	global_atomic_add v4, v0, v1, s[6:7] sc0
	s_mov_b32 s13, 0
	s_waitcnt lgkmcnt(0)
	v_readfirstlane_b32 s10, v2
	v_readfirstlane_b32 s11, v3
	v_mov_b32_e32 v0, 0x3400
	s_nop 3
	s_mul_i32 s10, s10, 8
	s_mul_i32 s11, s11, 8
	s_waitcnt vmcnt(0)
	v_readfirstlane_b32 s12, v4
	s_nop 3
	s_add_u32 s12, s12, 1
	s_cmp_lg_u32 s12, s10
	s_cbranch_scc1 .Lgb8_poll
	buffer_wbl2 sc1
	s_waitcnt vmcnt(0)
	global_atomic_add v0, v1, s[84:85]

.Lgb8_wait:
	s_barrier
.LBB0_1015:
	s_cmp_gt_i32 s60, 9
	s_cselect_b64 s[2:3], -1, 0
	s_cmp_lt_i32 s61, 9
	s_cselect_b64 s[4:5], -1, 0
	s_or_b64 s[2:3], s[2:3], s[4:5]
	s_and_b64 vcc, exec, s[2:3]
	s_cbranch_vccnz .LBB0_1075
	s_load_dwordx2 s[4:5], s[0:1], 0xe0
	s_load_dword s16, s[0:1], 0xf0
	v_and_b32_e32 v240, 63, v162
	v_lshrrev_b32_e32 v247, 6, v162
	v_lshrrev_b32_e32 v242, 3, v240
	v_lshl_add_u32 v242, v247, 5, v242
	v_and_b32_e32 v243, 7, v240
	v_lshrrev_b32_e32 v244, 4, v240
	v_xor_b32_e32 v243, v243, v244
	v_lshlrev_b32_e32 v243, 4, v243
	v_mov_b32_e32 v241, 0x1600
	v_mad_u32_u24 v248, v242, v241, v243
	v_xor_b32_e32 v249, 64, v248
	v_add_u32_e32 v249, 0xb000, v249
	v_add_u32_e32 v250, 0x16000, v248
	v_xor_b32_e32 v251, 64, v248
	v_add_u32_e32 v251, 0x21000, v251
	v_and_b32_e32 v241, 15, v240
	v_lshrrev_b32_e32 v242, 1, v241
	v_xor_b32_e32 v242, v242, v244
	v_lshlrev_b32_e32 v242, 4, v242
	v_lshl_or_b32 v242, v241, 7, v242
	v_lshrrev_b32_e32 v243, 1, v247
	v_lshl_or_b32 v252, v243, 13, v242
	v_xor_b32_e32 v253, 64, v252
	v_and_b32_e32 v243, 1, v247
	v_lshl_or_b32 v254, v243, 13, v242
	v_xor_b32_e32 v255, 64, v254
	v_and_b32_e32 v240, 63, v162
	v_and_b32_e32 v241, 15, v240
	v_lshrrev_b32_e32 v242, 4, v240
	v_lshrrev_b32_e32 v243, 1, v247
	v_and_b32_e32 v244, 1, v247
	v_lshl_or_b32 v245, v244, 6, v241
	v_lshlrev_b32_e32 v243, 4, v243
	v_add_u32_e32 v243, v243, v242
	v_lshl_add_u32 v246, v243, 12, v245
	v_lshlrev_b32_e32 v246, 2, v246
	v_lshlrev_b32_e32 v245, 2, v245
	s_waitcnt lgkmcnt(0)
	s_add_u32 s26, s4, 0x9b7a100
	s_addc_u32 s27, s5, 0
	s_add_u32 s28, s4, 0x5080000
	s_addc_u32 s29, s5, 0
	s_mov_b32 s15, s58

.LBB0_1079:
	s_or_b64 exec, exec, s[10:11]
	s_cmp_lt_u32 s61, 11
	s_cbranch_scc1 .LBB0_1133
	s_waitcnt vmcnt(0) lgkmcnt(0)
	s_barrier
	v_readfirstlane_b32 s2, v162
	s_lshl_b32 s3, s33, 8
	s_add_u32 s6, s84, s3
	s_addc_u32 s7, s85, 0
	s_cmp_lg_u32 s2, 0
	s_cbranch_scc1 .Lgb10_wait
	s_mov_b64 s[8:9], exec
	s_mov_b64 exec, 1
	v_mov_b32_e32 v0, 0x12000
	ds_read_b64 v[2:3], v0
	v_mov_b32_e32 v0, 0x1400
	v_mov_b32_e32 v1, 1
	global_atomic_add v4, v0, v1, s[6:7] sc0
	s_mov_b32 s13, 0
	s_waitcnt lgkmcnt(0)
	v_readfirstlane_b32 s10, v2
	v_readfirstlane_b32 s11, v3
	v_mov_b32_e32 v0, 0x3400
	s_nop 3
	s_mul_i32 s10, s10, 9
	s_mul_i32 s11, s11, 9
	s_waitcnt vmcnt(0)
	v_readfirstlane_b32 s12, v4
	s_nop 3
	s_add_u32 s12, s12, 1
	s_cmp_lg_u32 s12, s10
	s_cbranch_scc1 .Lgb10_poll
	buffer_wbl2 sc1
	s_waitcnt vmcnt(0)
	global_atomic_add v0, v1, s[84:85]

.Lgb10_wait:
	s_barrier
.LBB0_1133:
	s_cmp_gt_i32 s60, 11
	s_cselect_b64 s[2:3], -1, 0
	s_cmp_lt_i32 s61, 11
	s_cselect_b64 s[4:5], -1, 0
	s_or_b64 s[2:3], s[2:3], s[4:5]
	s_and_b64 vcc, exec, s[2:3]
	s_cbranch_vccnz .LBB0_1196
	s_mov_b64 s[4:5], s[0:1]
	s_cmpk_gt_i32 s58, 0x3ff
	s_cbranch_scc1 .LBB0_1142
	s_load_dwordx2 s[4:5], s[4:5], 0xe0
	v_lshrrev_b32_e32 v10, 3, v162
	v_lshlrev_b32_e32 v0, 3, v162
	v_mov_b32_e32 v1, 0
	v_and_b32_e32 v4, 56, v0
	v_lshlrev_b32_e32 v2, 9, v10
	v_mov_b32_e32 v3, v1
	v_xor_b32_e32 v11, v163, v162
	s_waitcnt lgkmcnt(0)
	v_lshl_add_u64 v[2:3], s[4:5], 0, v[2:3]
	v_lshlrev_b32_e32 v6, 1, v4
	v_mov_b32_e32 v7, v1
	v_lshl_add_u64 v[2:3], v[2:3], 0, v[6:7]
	v_lshlrev_b32_e32 v7, 4, v11
	v_and_b32_e32 v9, 15, v162
	s_add_u32 s2, s4, 0x8b7a100
	v_bfe_u32 v6, v162, 1, 3
	v_and_b32_e32 v7, 0x70, v7
	s_load_dword s10, s[0:1], 0xf0
	v_bfe_u32 v5, v162, 6, 1
	v_lshrrev_b32_e32 v8, 7, v162
	s_addc_u32 s3, s5, 0
	v_lshlrev_b32_e32 v0, 11, v10
	v_bitop3_b32 v6, v163, v6, 3 bitop3:0x6c
	v_lshl_or_b32 v10, v10, 7, v7
	v_lshlrev_b32_e32 v7, 7, v9
	v_lshl_or_b32 v13, v8, 13, v7
	v_lshl_or_b32 v7, v5, 13, v7
	v_lshlrev_b32_e32 v6, 4, v6
	s_add_u32 s11, s4, 0xbb7a100
	v_bfe_u32 v15, v162, 4, 2
	v_or_b32_e32 v11, v13, v6
	v_or_b32_e32 v12, v7, v6
	v_xor_b32_e32 v6, 64, v6
	s_addc_u32 s12, s5, 0
	s_mov_b64 s[6:7], 0x6ac0000
	v_or_b32_e32 v13, v13, v6
	v_or_b32_e32 v14, v7, v6
	v_lshlrev_b32_e32 v6, 6, v8
	v_lshlrev_b32_e32 v8, 2, v15
	s_add_u32 s13, s4, 0xab7a100
	v_lshl_add_u64 v[2:3], v[2:3], 0, s[6:7]
	s_addc_u32 s14, s5, 0
	v_lshl_or_b32 v15, v5, 6, v9
	s_lshl_b32 s15, s58, 1
	s_waitcnt lgkmcnt(0)
	s_lshl_b32 s16, s10, 1
	s_lshl_b32 s17, s58, 7
	s_lshl_b32 s18, s10, 7
	s_mov_b32 s5, 0
	v_lshlrev_b32_e32 v4, 1, v4
	v_mov_b32_e32 v5, v1
	s_mov_b32 s19, 0x10000
	s_mov_b32 s20, 0x20000
	s_mov_b32 s21, 0x30000
	s_movk_i32 s22, 0x4000
	s_mov_b32 s23, 0x8000
	s_mov_b32 s24, 0xc000
	v_lshlrev_b32_e32 v6, 1, v6
	v_mov_b32_e32 v7, v1
	v_lshlrev_b32_e32 v8, 1, v8
	v_mov_b32_e32 v9, v1
	s_mov_b32 s25, s58
	s_branch .LBB0_1138

.LBB0_1142:
	s_cmp_lt_i32 s61, 12
	s_cbranch_scc1 .LBB0_1196
	s_waitcnt vmcnt(0) lgkmcnt(0)
	s_barrier
	v_readfirstlane_b32 s2, v162
	s_lshl_b32 s3, s33, 8
	s_add_u32 s6, s84, s3
	s_addc_u32 s7, s85, 0
	s_cmp_lg_u32 s2, 0
	s_cbranch_scc1 .Lgb11_wait
	s_mov_b64 s[8:9], exec
	s_mov_b64 exec, 1
	v_mov_b32_e32 v0, 0x12000
	ds_read_b64 v[2:3], v0
	v_mov_b32_e32 v0, 0x1400
	v_mov_b32_e32 v1, 1
	global_atomic_add v4, v0, v1, s[6:7] sc0
	s_mov_b32 s13, 0
	s_waitcnt lgkmcnt(0)
	v_readfirstlane_b32 s10, v2
	v_readfirstlane_b32 s11, v3
	v_mov_b32_e32 v0, 0x3400
	s_nop 3
	s_mul_i32 s10, s10, 10
	s_mul_i32 s11, s11, 10
	s_waitcnt vmcnt(0)
	v_readfirstlane_b32 s12, v4
	s_nop 3
	s_add_u32 s12, s12, 1
	s_cmp_lg_u32 s12, s10
	s_cbranch_scc1 .Lgb11_poll
	buffer_wbl2 sc1
	s_waitcnt vmcnt(0)
	global_atomic_add v0, v1, s[84:85]

.Lgb11_wait:
	s_barrier
.LBB0_1196:
	s_cmp_gt_i32 s60, 12
	s_cselect_b64 s[2:3], -1, 0
	s_cmp_lt_i32 s61, 12
	s_cselect_b64 s[4:5], -1, 0
	s_or_b64 s[2:3], s[2:3], s[4:5]
	s_and_b64 vcc, exec, s[2:3]
	s_cbranch_vccnz .LBB0_1260
	s_mov_b64 s[4:5], s[0:1]
	s_cmpk_gt_i32 s58, 0x1ff
	s_cbranch_scc1 .LBB0_1206
	s_load_dwordx2 s[4:5], s[4:5], 0xe0
	v_xor_b32_e32 v5, v163, v162
	v_lshlrev_b32_e32 v5, 4, v5
	v_and_b32_e32 v3, 15, v162
	v_lshrrev_b32_e32 v129, 3, v162
	v_and_b32_e32 v5, 0x70, v5
	v_lshrrev_b32_e32 v2, 7, v162
	v_lshl_or_b32 v136, v129, 7, v5
	v_lshlrev_b32_e32 v5, 7, v3
	v_bfe_u32 v4, v162, 4, 2
	v_mov_b32_e32 v97, 0
	v_lshl_or_b32 v7, v2, 13, v5
	v_lshlrev_b32_e32 v2, 6, v2
	v_lshlrev_b32_e32 v96, 1, v3
	v_lshl_or_b32 v141, v4, 2, v2
	s_waitcnt lgkmcnt(0)
	v_lshl_add_u64 v[2:3], s[4:5], 0, v[96:97]
	s_mov_b64 s[2:3], 0x9b7a100
	v_lshl_add_u64 v[98:99], v[2:3], 0, s[2:3]
	s_add_u32 s3, s4, 0x6a80000
	s_addc_u32 s44, s5, 0
	s_add_u32 s45, s4, 0xab7a100
	v_bfe_u32 v6, v162, 1, 3
	s_load_dword s2, s[0:1], 0xf0
	s_addc_u32 s46, s5, 0
	v_bfe_u32 v1, v162, 6, 1
	v_bitop3_b32 v6, v163, v6, 3 bitop3:0x6c
	s_add_u32 s47, s4, 0x6680000
	v_lshlrev_b32_e32 v0, 3, v162
	v_lshl_or_b32 v5, v1, 13, v5
	v_lshlrev_b32_e32 v6, 4, v6
	s_addc_u32 s48, s5, 0
	v_and_b32_e32 v0, 56, v0
	v_or_b32_e32 v137, v7, v6
	v_or_b32_e32 v138, v5, v6
	v_xor_b32_e32 v6, 64, v6
	v_lshlrev_b32_e32 v1, 6, v1
	s_add_u32 s49, s4, 0xbb7a100
	v_or_b32_e32 v139, v7, v6
	v_or_b32_e32 v140, v5, v6
	s_addc_u32 s50, s5, 0
	s_mov_b32 s5, 0
	v_lshlrev_b32_e32 v100, 1, v0
	v_mov_b32_e32 v101, v97
	s_mov_b64 s[6:7], 0x100
	v_lshlrev_b32_e32 v142, 1, v1
	s_mov_b64 s[8:9], 0x1000
	s_mov_b64 s[10:11], 0x1800
	s_mov_b64 s[12:13], 0x8000
	s_mov_b32 s51, 0x8000
	s_mov_b64 s[14:15], 0x8800
	s_mov_b64 s[16:17], 0x9000
	s_mov_b32 s54, 0x9000
	s_mov_b64 s[18:19], 0x9800
	s_mov_b64 s[20:21], 0x10000
	s_mov_b32 s55, 0x10000
	s_mov_b64 s[22:23], 0x10800
	s_mov_b64 s[24:25], 0x11000
	s_mov_b32 s59, 0x11000
	s_mov_b64 s[26:27], 0x11800
	s_mov_b64 s[28:29], 0x18000
	s_mov_b32 s62, 0x18000
	s_mov_b64 s[30:31], 0x18800
	s_mov_b64 s[34:35], 0x19000
	s_mov_b32 s63, 0x19000
	s_mov_b64 s[36:37], 0x19800
	s_mov_b32 s64, s58

.LBB0_1206:
	s_cmp_lt_i32 s61, 13
	s_cbranch_scc1 .LBB0_1260
	s_waitcnt vmcnt(0) lgkmcnt(0)
	s_barrier
	v_readfirstlane_b32 s2, v162
	s_lshl_b32 s3, s33, 8
	s_add_u32 s6, s84, s3
	s_addc_u32 s7, s85, 0
	s_cmp_lg_u32 s2, 0
	s_cbranch_scc1 .Lgb12_wait
	s_mov_b64 s[8:9], exec
	s_mov_b64 exec, 1
	v_mov_b32_e32 v0, 0x12000
	ds_read_b64 v[2:3], v0
	v_mov_b32_e32 v0, 0x1400
	v_mov_b32_e32 v1, 1
	global_atomic_add v4, v0, v1, s[6:7] sc0
	s_mov_b32 s13, 0
	s_waitcnt lgkmcnt(0)
	v_readfirstlane_b32 s10, v2
	v_readfirstlane_b32 s11, v3
	v_mov_b32_e32 v0, 0x3400
	s_nop 3
	s_mul_i32 s10, s10, 11
	s_mul_i32 s11, s11, 11
	s_waitcnt vmcnt(0)
	v_readfirstlane_b32 s12, v4
	s_nop 3
	s_add_u32 s12, s12, 1
	s_cmp_lg_u32 s12, s10
	s_cbranch_scc1 .Lgb12_poll
	buffer_wbl2 sc1
	s_waitcnt vmcnt(0)
	global_atomic_add v0, v1, s[84:85]

.Lgb12_wait:
	s_barrier
.LBB0_1260:
	s_cmp_gt_i32 s60, 13
	s_cselect_b64 s[2:3], -1, 0
	s_cmp_lt_i32 s61, 13
	s_cselect_b64 s[4:5], -1, 0
	s_or_b64 s[2:3], s[2:3], s[4:5]
	s_and_b64 vcc, exec, s[2:3]
	s_cbranch_vccnz .LBB0_1328
	s_load_dwordx2 s[4:5], s[0:1], 0xe0
	s_load_dword s16, s[0:1], 0xf0
	s_load_dwordx2 s[24:25], s[0:1], 0xb8
	v_and_b32_e32 v240, 63, v162
	v_lshrrev_b32_e32 v247, 6, v162
	v_lshrrev_b32_e32 v242, 3, v240
	v_lshl_add_u32 v242, v247, 5, v242
	v_and_b32_e32 v243, 7, v240
	v_lshrrev_b32_e32 v244, 4, v240
	v_xor_b32_e32 v243, v243, v244
	v_lshlrev_b32_e32 v243, 4, v243
	v_mov_b32_e32 v241, 0x800
	v_mad_u32_u24 v248, v242, v241, v243
	v_xor_b32_e32 v249, 64, v248
	v_add_u32_e32 v249, 0x4000, v249
	v_add_u32_e32 v250, 0x8000, v248
	v_xor_b32_e32 v251, 64, v248
	v_add_u32_e32 v251, 0xc000, v251
	v_and_b32_e32 v241, 15, v240
	v_lshrrev_b32_e32 v242, 1, v241
	v_xor_b32_e32 v242, v242, v244
	v_lshlrev_b32_e32 v242, 4, v242
	v_lshl_or_b32 v242, v241, 7, v242
	v_lshrrev_b32_e32 v243, 1, v247
	v_lshl_or_b32 v252, v243, 13, v242
	v_xor_b32_e32 v253, 64, v252
	v_and_b32_e32 v243, 1, v247
	v_lshl_or_b32 v254, v243, 13, v242
	v_xor_b32_e32 v255, 64, v254
	v_and_b32_e32 v240, 63, v162
	v_and_b32_e32 v241, 15, v240
	v_lshrrev_b32_e32 v242, 4, v240
	v_lshrrev_b32_e32 v243, 1, v247
	v_and_b32_e32 v244, 1, v247
	v_lshl_or_b32 v245, v244, 6, v241
	v_lshlrev_b32_e32 v243, 4, v243
	v_add_u32_e32 v243, v243, v242
	v_lshl_add_u32 v246, v243, 12, v245
	v_lshlrev_b32_e32 v246, 2, v246
	v_lshlrev_b32_e32 v245, 2, v245
	s_waitcnt lgkmcnt(0)
	s_add_u32 s26, s4, 0x9b7a100
	s_addc_u32 s27, s5, 0
	s_add_u32 s28, s4, 0x2080000
	s_addc_u32 s29, s5, 0
	s_mov_b32 s15, s58

.LBB0_1332:
	s_or_b64 exec, exec, s[10:11]
	s_cmp_lt_u32 s61, 15
	s_cbranch_scc1 .LBB0_1386
	s_waitcnt vmcnt(0) lgkmcnt(0)
	s_barrier
	v_readfirstlane_b32 s2, v162
	s_lshl_b32 s3, s33, 8
	s_add_u32 s6, s84, s3
	s_addc_u32 s7, s85, 0
	s_cmp_lg_u32 s2, 0
	s_cbranch_scc1 .Lgb14_wait
	s_mov_b64 s[8:9], exec
	s_mov_b64 exec, 1
	v_mov_b32_e32 v0, 0x12000
	ds_read_b64 v[2:3], v0
	v_mov_b32_e32 v0, 0x1400
	v_mov_b32_e32 v1, 1
	global_atomic_add v4, v0, v1, s[6:7] sc0
	s_mov_b32 s13, 0
	s_waitcnt lgkmcnt(0)
	v_readfirstlane_b32 s10, v2
	v_readfirstlane_b32 s11, v3
	v_mov_b32_e32 v0, 0x3400
	s_nop 3
	s_mul_i32 s10, s10, 12
	s_mul_i32 s11, s11, 12
	s_waitcnt vmcnt(0)
	v_readfirstlane_b32 s12, v4
	s_nop 3
	s_add_u32 s12, s12, 1
	s_cmp_lg_u32 s12, s10
	s_cbranch_scc1 .Lgb14_poll
	buffer_wbl2 sc1
	s_waitcnt vmcnt(0)
	global_atomic_add v0, v1, s[84:85]

.Lgb14_wait:
	s_barrier
.LBB0_1386:
	s_cmp_gt_i32 s60, 15
	s_cselect_b64 s[2:3], -1, 0
	s_cmp_lt_i32 s61, 15
	s_cselect_b64 s[4:5], -1, 0
	s_or_b64 s[2:3], s[2:3], s[4:5]
	s_and_b64 vcc, exec, s[2:3]
	s_cbranch_vccnz .LBB0_1450
	s_load_dwordx2 s[4:5], s[0:1], 0xe0
	s_load_dword s16, s[0:1], 0xf0
	v_and_b32_e32 v240, 63, v162
	v_lshrrev_b32_e32 v247, 6, v162
	v_lshrrev_b32_e32 v242, 3, v240
	v_lshl_add_u32 v242, v247, 5, v242
	v_and_b32_e32 v243, 7, v240
	v_lshrrev_b32_e32 v244, 4, v240
	v_xor_b32_e32 v243, v243, v244
	v_lshlrev_b32_e32 v243, 4, v243
	v_mov_b32_e32 v241, 0x800
	v_mad_u32_u24 v248, v242, v241, v243
	v_xor_b32_e32 v249, 64, v248
	v_add_u32_e32 v249, 0x4000, v249
	v_add_u32_e32 v250, 0x8000, v248
	v_xor_b32_e32 v251, 64, v248
	v_add_u32_e32 v251, 0xc000, v251
	v_and_b32_e32 v241, 15, v240
	v_lshrrev_b32_e32 v242, 1, v241
	v_xor_b32_e32 v242, v242, v244
	v_lshlrev_b32_e32 v242, 4, v242
	v_lshl_or_b32 v242, v241, 7, v242
	v_lshrrev_b32_e32 v243, 1, v247
	v_lshl_or_b32 v252, v243, 13, v242
	v_xor_b32_e32 v253, 64, v252
	v_and_b32_e32 v243, 1, v247
	v_lshl_or_b32 v254, v243, 13, v242
	v_xor_b32_e32 v255, 64, v254
	v_and_b32_e32 v240, 63, v162
	v_and_b32_e32 v241, 15, v240
	v_lshrrev_b32_e32 v242, 4, v240
	v_mul_u32_u24_e32 v245, 0x1400, v247
	v_mul_u32_u24_e32 v243, 80, v241
	v_add_u32_e32 v243, v243, v245
	v_lshl_add_u32 v244, v242, 3, v243
	v_lshrrev_b32_e32 v243, 2, v240
	v_mul_u32_u24_e32 v246, 80, v243
	v_add_u32_e32 v246, v246, v245
	v_and_b32_e32 v241, 3, v240
	v_lshl_add_u32 v246, v241, 4, v246
	v_mov_b32_e32 v245, v244
	v_lshrrev_b32_e32 v242, 1, v247
	v_lshl_add_u32 v243, v242, 6, v243
	v_mov_b32_e32 v242, 0x1600
	v_mul_u32_u24_e32 v243, v243, v242
	v_and_b32_e32 v242, 1, v247
	v_lshl_add_u32 v243, v242, 6, v243
	v_lshl_add_u32 v239, v241, 4, v243
	s_waitcnt lgkmcnt(0)
	s_add_u32 s26, s4, 0x8b7a100
	s_addc_u32 s27, s5, 0
	s_add_u32 s28, s4, 0x2f80000
	s_addc_u32 s29, s5, 0
	s_mov_b32 s15, s58

.Lf15_end:
.LBB0_1396:
	s_cmp_lt_i32 s61, 16
	s_cbranch_scc1 .LBB0_1450
	s_waitcnt vmcnt(0) lgkmcnt(0)
	s_barrier
	v_readfirstlane_b32 s2, v162
	s_lshl_b32 s3, s33, 8
	s_add_u32 s6, s84, s3
	s_addc_u32 s7, s85, 0
	s_cmp_lg_u32 s2, 0
	s_cbranch_scc1 .Lgb15_wait
	s_mov_b64 s[8:9], exec
	s_mov_b64 exec, 1
	v_mov_b32_e32 v0, 0x12000
	ds_read_b64 v[2:3], v0
	v_mov_b32_e32 v0, 0x1400
	v_mov_b32_e32 v1, 1
	global_atomic_add v4, v0, v1, s[6:7] sc0
	s_mov_b32 s13, 0
	s_waitcnt lgkmcnt(0)
	v_readfirstlane_b32 s10, v2
	v_readfirstlane_b32 s11, v3
	v_mov_b32_e32 v0, 0x3400
	s_nop 3
	s_mul_i32 s10, s10, 13
	s_mul_i32 s11, s11, 13
	s_waitcnt vmcnt(0)
	v_readfirstlane_b32 s12, v4
	s_nop 3
	s_add_u32 s12, s12, 1
	s_cmp_lg_u32 s12, s10
	s_cbranch_scc1 .Lgb15_poll
	buffer_wbl2 sc1
	s_waitcnt vmcnt(0)
	global_atomic_add v0, v1, s[84:85]

.Lgb15_wait:
	s_barrier
.LBB0_1450:
	s_cmp_gt_i32 s60, 16
	s_cselect_b64 s[2:3], -1, 0
	s_cmp_lt_i32 s61, 16
	s_cselect_b64 s[4:5], -1, 0
	s_or_b64 s[2:3], s[2:3], s[4:5]
	s_and_b64 vcc, exec, s[2:3]
	s_cbranch_vccnz .LBB0_1510
	s_load_dwordx2 s[4:5], s[0:1], 0xe0
	s_load_dword s16, s[0:1], 0xf0
	v_and_b32_e32 v240, 63, v162
	v_lshrrev_b32_e32 v247, 6, v162
	v_lshrrev_b32_e32 v242, 3, v240
	v_lshl_add_u32 v242, v247, 5, v242
	v_and_b32_e32 v243, 7, v240
	v_lshrrev_b32_e32 v244, 4, v240
	v_xor_b32_e32 v243, v243, v244
	v_lshlrev_b32_e32 v243, 4, v243
	v_mov_b32_e32 v241, 0x1600
	v_mad_u32_u24 v248, v242, v241, v243
	v_xor_b32_e32 v249, 64, v248
	v_add_u32_e32 v249, 0xb000, v249
	v_add_u32_e32 v250, 0x16000, v248
	v_xor_b32_e32 v251, 64, v248
	v_add_u32_e32 v251, 0x21000, v251
	v_and_b32_e32 v241, 15, v240
	v_lshrrev_b32_e32 v242, 1, v241
	v_xor_b32_e32 v242, v242, v244
	v_lshlrev_b32_e32 v242, 4, v242
	v_lshl_or_b32 v242, v241, 7, v242
	v_lshrrev_b32_e32 v243, 1, v247
	v_lshl_or_b32 v252, v243, 13, v242
	v_xor_b32_e32 v253, 64, v252
	v_and_b32_e32 v243, 1, v247
	v_lshl_or_b32 v254, v243, 13, v242
	v_xor_b32_e32 v255, 64, v254
	v_and_b32_e32 v240, 63, v162
	v_and_b32_e32 v241, 15, v240
	v_lshrrev_b32_e32 v242, 4, v240
	v_lshrrev_b32_e32 v243, 1, v247
	v_and_b32_e32 v244, 1, v247
	v_lshl_or_b32 v245, v244, 6, v241
	v_lshlrev_b32_e32 v243, 4, v243
	v_add_u32_e32 v243, v243, v242
	v_lshl_add_u32 v246, v243, 12, v245
	v_lshlrev_b32_e32 v246, 2, v246
	v_lshlrev_b32_e32 v245, 2, v245
	s_waitcnt lgkmcnt(0)
	s_add_u32 s26, s4, 0x9b7a100
	s_addc_u32 s27, s5, 0
	s_add_u32 s28, s4, 0x5600000
	s_addc_u32 s29, s5, 0
	s_mov_b32 s15, s58

.LBB0_1519:
	s_or_b64 exec, exec, s[4:5]
	s_cmp_lt_u32 s61, 18
	s_cbranch_scc1 .LBB0_1573
	s_waitcnt vmcnt(0) lgkmcnt(0)
	s_barrier
	v_readfirstlane_b32 s2, v162
	s_lshl_b32 s3, s33, 8
	s_add_u32 s6, s84, s3
	s_addc_u32 s7, s85, 0
	s_cmp_lg_u32 s2, 0
	s_cbranch_scc1 .Lgb17_wait
	s_mov_b64 s[8:9], exec
	s_mov_b64 exec, 1
	v_mov_b32_e32 v0, 0x12000
	ds_read_b64 v[2:3], v0
	v_mov_b32_e32 v0, 0x1400
	v_mov_b32_e32 v1, 1
	global_atomic_add v4, v0, v1, s[6:7] sc0
	s_mov_b32 s13, 0
	s_waitcnt lgkmcnt(0)
	v_readfirstlane_b32 s10, v2
	v_readfirstlane_b32 s11, v3
	v_mov_b32_e32 v0, 0x3400
	s_nop 3
	s_mul_i32 s10, s10, 14
	s_mul_i32 s11, s11, 14
	s_waitcnt vmcnt(0)
	v_readfirstlane_b32 s12, v4
	s_nop 3
	s_add_u32 s12, s12, 1
	s_cmp_lg_u32 s12, s10
	s_cbranch_scc1 .Lgb17_poll
	buffer_wbl2 sc1
	s_waitcnt vmcnt(0)
	global_atomic_add v0, v1, s[84:85]

.Lgb17_wait:
	s_barrier
.LBB0_1573:
	s_cmp_gt_i32 s60, 18
	s_waitcnt lgkmcnt(0)
	s_cselect_b64 s[2:3], -1, 0
	s_cmp_lt_i32 s61, 18
	s_cselect_b64 s[4:5], -1, 0
	s_or_b64 s[2:3], s[2:3], s[4:5]
	s_and_b64 vcc, exec, s[2:3]
	s_cbranch_vccnz .LBB0_1845
	s_mov_b64 s[76:77], s[84:85]
	s_mov_b64 s[14:15], s[0:1]
	s_cmpk_gt_i32 s58, 0xc3f
	s_cbranch_scc1 .LBB0_1791
	s_load_dwordx2 s[16:17], s[14:15], 0xe0
	s_load_dword s3, s[0:1], 0xf0
	v_lshrrev_b32_e32 v9, 3, v162
	v_lshlrev_b32_e32 v0, 3, v162
	v_and_b32_e32 v0, 56, v0
	s_waitcnt lgkmcnt(0)
	s_add_u32 s18, s16, 0x8b7a100
	s_addc_u32 s19, s17, 0
	s_add_u32 s20, s16, 0xc40000
	v_mov_b32_e32 v99, 0
	v_lshlrev_b32_e32 v98, 11, v9
	s_addc_u32 s21, s17, 0
	v_lshl_add_u64 v[4:5], s[18:19], 0, v[98:99]
	v_lshlrev_b32_e32 v6, 1, v0
	v_mov_b32_e32 v7, v99
	v_xor_b32_e32 v10, v163, v162
	v_lshl_add_u64 v[100:101], v[4:5], 0, v[6:7]
	v_lshl_add_u64 v[4:5], s[20:21], 0, v[98:99]
	v_lshl_add_u64 v[102:103], v[4:5], 0, v[6:7]
	v_lshlrev_b32_e32 v5, 4, v10
	v_and_b32_e32 v96, 15, v162
	v_bfe_u32 v4, v162, 1, 3
	v_and_b32_e32 v5, 0x70, v5
	v_bfe_u32 v1, v162, 6, 1
	v_lshrrev_b32_e32 v3, 7, v162
	v_bitop3_b32 v4, v163, v4, 3 bitop3:0x6c
	v_lshl_or_b32 v145, v9, 7, v5
	v_lshlrev_b32_e32 v5, 7, v96
	v_lshl_or_b32 v6, v3, 13, v5
	v_lshl_or_b32 v5, v1, 13, v5
	v_lshlrev_b32_e32 v4, 4, v4
	v_or_b32_e32 v170, v6, v4
	v_or_b32_e32 v171, v5, v4
	v_xor_b32_e32 v4, 64, v4
	v_or_b32_e32 v172, v6, v4
	v_or_b32_e32 v173, v5, v4
	v_lshlrev_b32_e32 v4, 2, v96
	v_mov_b32_e32 v5, v99
	v_lshl_add_u64 v[4:5], s[16:17], 0, v[4:5]
	s_mov_b64 s[6:7], 0x1237a100
	v_lshl_add_u64 v[104:105], v[4:5], 0, s[6:7]
	s_mov_b64 s[6:7], 0x1237a140
	v_lshl_add_u64 v[106:107], v[4:5], 0, s[6:7]
	v_lshlrev_b32_e32 v4, 7, v1
	v_mov_b32_e32 v5, v99
	v_lshl_add_u64 v[4:5], s[16:17], 0, v[4:5]
	s_mov_b64 s[6:7], 0xdb7a100
	s_add_u32 s24, s16, 0xef7a100
	v_lshl_add_u64 v[108:109], v[4:5], 0, s[6:7]
	s_mov_b64 s[6:7], 0xe37a100
	v_lshlrev_b32_e32 v175, 6, v1
	v_cmp_eq_u32_e64 s[4:5], 0, v1
	s_addc_u32 s25, s17, 0
	v_lshl_add_u64 v[110:111], v[4:5], 0, s[6:7]
	v_lshlrev_b32_e32 v4, 1, v96
	v_mov_b32_e32 v5, v99
	v_and_b32_e32 v1, 7, v162
	s_add_u32 s26, s16, 0x6b00000
	v_lshl_add_u64 v[4:5], s[16:17], 0, v[4:5]
	s_mov_b64 s[6:7], 0x9b7a100
	v_lshl_or_b32 v98, v1, 4, v98
	s_addc_u32 s27, s17, 0
	v_lshl_add_u64 v[112:113], v[4:5], 0, s[6:7]
	v_lshl_add_u64 v[4:5], s[16:17], 0, v[98:99]
	s_mov_b64 s[6:7], 0xc40200
	v_bfe_u32 v8, v162, 4, 2
	v_lshlrev_b32_e32 v2, 10, v9
	v_lshlrev_b32_e32 v3, 6, v3
	s_add_u32 s28, s16, 0xcb7a100
	v_lshl_add_u64 v[114:115], v[4:5], 0, s[6:7]
	s_mov_b64 s[6:7], 0x8b7a300
	v_lshl_or_b32 v174, v8, 2, v3
	s_mov_b32 s23, 0
	v_or_b32_e32 v176, v175, v96
	s_addc_u32 s29, s17, 0
	s_lshl_b32 s68, s58, 1
	s_lshl_b32 s69, s3, 1
	v_lshl_add_u64 v[116:117], v[4:5], 0, s[6:7]
	s_lshl_b32 s70, s58, 7
	s_lshl_b32 s71, s3, 7
	s_mov_b64 s[8:9], 0
	s_mov_b32 s73, 0x10000
	s_mov_b64 s[30:31], 0x100
	s_mov_b64 s[34:35], 0x10000
	s_mov_b64 s[36:37], 0x10100
	s_mov_b64 s[38:39], 0x20000
	s_mov_b64 s[40:41], 0x20100
	s_mov_b64 s[42:43], 0x30000
	s_mov_b64 s[44:45], 0x30100
	v_lshlrev_b32_e32 v118, 1, v2
	v_mov_b32_e32 v119, v99
	v_lshlrev_b32_e32 v120, 1, v0
	v_mov_b32_e32 v121, v99
	s_mov_b64 s[46:47], 0x780
	s_brev_b32 s75, 32
	s_mov_b32 s59, 0x3fff80
	s_mov_b32 s78, 0xf786000
	s_mov_b64 s[48:49], 0xf79e500
	s_movk_i32 s79, 0xf400
	s_movk_i32 s80, 0x7e00
	s_mov_b64 s[50:51], 0x2000000
	s_movk_i32 s81, 0xf0
	s_movk_i32 s83, 0x600
	s_movk_i32 s84, 0x200
	s_movk_i32 s85, 0x3d0
	s_movk_i32 s86, 0x3e0
	s_movk_i32 s87, 0x3f0
	s_movk_i32 s88, 0x3c0
	s_mov_b32 s90, 0xab89000
	s_mov_b32 s91, 0xab8a000
	s_mov_b32 s92, 0xab8b000
	s_mov_b32 s93, 0xab8c000
	s_mov_b32 s94, 0xab99000
	s_mov_b32 s95, 0xab9a000
	s_mov_b32 s96, 0xab9b000
	s_mov_b32 s97, 0xab9c000
	s_mov_b32 s89, 0xaba9000
	s_mov_b32 s72, 0xabaa000
	s_mov_b32 s74, 0xabab000
	s_mov_b32 s82, 0xabac000
	s_mov_b64 s[54:55], 0x60
	v_mov_b32_e32 v177, 0x100000
	s_mov_b32 s2, s58
	v_and_b32_e32 v240, 63, v162
	v_lshrrev_b32_e32 v247, 6, v162
	v_lshrrev_b32_e32 v242, 3, v240
	v_lshl_add_u32 v242, v247, 5, v242
	v_and_b32_e32 v243, 7, v240
	v_lshrrev_b32_e32 v244, 4, v240
	v_xor_b32_e32 v243, v243, v244
	v_lshlrev_b32_e32 v243, 4, v243
	v_mov_b32_e32 v241, 0x800
	v_mad_u32_u24 v248, v242, v241, v243
	v_xor_b32_e32 v249, 64, v248
	v_add_u32_e32 v249, 0x4000, v249
	v_add_u32_e32 v250, 0x8000, v248
	v_xor_b32_e32 v251, 64, v248
	v_add_u32_e32 v251, 0xc000, v251
	v_and_b32_e32 v241, 15, v240
	v_lshrrev_b32_e32 v242, 1, v241
	v_xor_b32_e32 v242, v242, v244
	v_lshlrev_b32_e32 v242, 4, v242
	v_lshl_or_b32 v242, v241, 7, v242
	v_lshrrev_b32_e32 v243, 1, v247
	v_lshl_or_b32 v252, v243, 13, v242
	v_xor_b32_e32 v253, 64, v252
	v_and_b32_e32 v243, 1, v247
	v_lshl_or_b32 v254, v243, 13, v242
	v_xor_b32_e32 v255, 64, v254
	s_load_dwordx2 s[6:7], s[0:1], 0xe0
	s_load_dword s22, s[0:1], 0xf0
	v_and_b32_e32 v155, 63, v162
	v_lshrrev_b32_e32 v154, 6, v162
	v_and_b32_e32 v152, 15, v155
	v_lshrrev_b32_e32 v153, 4, v155
	v_lshlrev_b32_e32 v153, 4, v153
	v_lshl_add_u32 v153, v154, 9, v153
	v_lshl_add_u32 v152, v152, 11, v153
	s_waitcnt lgkmcnt(0)
	s_mov_b32 s32, s58

.LBB0_1791:
	s_cmp_lt_i32 s61, 19
	s_mov_b64 s[84:85], s[76:77]
	s_cbranch_scc1 .LBB0_1845
	s_waitcnt vmcnt(0) lgkmcnt(0)
	s_barrier
	v_readfirstlane_b32 s2, v162
	s_lshl_b32 s3, s33, 8
	s_add_u32 s6, s84, s3
	s_addc_u32 s7, s85, 0
	s_cmp_lg_u32 s2, 0
	s_cbranch_scc1 .Lgb18_wait
	s_mov_b64 s[8:9], exec
	s_mov_b64 exec, 1
	v_mov_b32_e32 v0, 0x12000
	ds_read_b64 v[2:3], v0
	v_mov_b32_e32 v0, 0x1400
	v_mov_b32_e32 v1, 1
	global_atomic_add v4, v0, v1, s[6:7] sc0
	s_mov_b32 s13, 0
	s_waitcnt lgkmcnt(0)
	v_readfirstlane_b32 s10, v2
	v_readfirstlane_b32 s11, v3
	v_mov_b32_e32 v0, 0x3400
	s_nop 3
	s_mul_i32 s10, s10, 15
	s_mul_i32 s11, s11, 15
	s_waitcnt vmcnt(0)
	v_readfirstlane_b32 s12, v4
	s_nop 3
	s_add_u32 s12, s12, 1
	s_cmp_lg_u32 s12, s10
	s_cbranch_scc1 .Lgb18_poll
	buffer_wbl2 sc1
	s_waitcnt vmcnt(0)
	global_atomic_add v0, v1, s[84:85]

.Lgb18_wait:
	s_barrier
.LBB0_1845:
	s_cmp_gt_i32 s60, 19
	s_cselect_b64 s[2:3], -1, 0
	s_cmp_lt_i32 s61, 19
	s_cselect_b64 s[4:5], -1, 0
	s_or_b64 s[2:3], s[2:3], s[4:5]
	s_and_b64 vcc, exec, s[2:3]
	s_cbranch_vccnz .LBB0_1918
	s_mov_b64 s[12:13], s[0:1]
	s_load_dword s2, s[0:1], 0xf0
	s_load_dwordx2 s[10:11], s[12:13], 0xe0
	s_add_u32 s6, s0, 0xf0
	s_mov_b32 s3, 0x200000
	s_addc_u32 s7, s1, 0
	s_waitcnt lgkmcnt(0)
	s_lshl_b32 s8, s2, 8
	v_cmp_gt_i32_e32 vcc, s3, v128
	s_and_saveexec_b64 s[14:15], vcc
	s_cbranch_execz .LBB0_1859
	s_load_dwordx4 s[48:51], s[0:1], 0x68
	s_load_dword s64, s[0:1], 0xf0
	v_lshlrev_b32_e32 v25, 4, v162
	v_lshlrev_b32_e32 v26, 5, v162
	s_waitcnt lgkmcnt(0)
	s_add_u32 s48, s48, 0xa000
	s_addc_u32 s49, s49, 0
	s_add_u32 s50, s50, 0x2000
	s_addc_u32 s51, s51, 0
	global_load_dwordx4 v[28:31], v26, s[48:49]
	global_load_dwordx4 v[32:35], v26, s[48:49] offset:16
	s_add_u32 s48, s48, 0x2000
	s_addc_u32 s49, s49, 0
	global_load_dwordx4 v[36:39], v26, s[48:49]
	global_load_dwordx4 v[40:43], v26, s[48:49] offset:16
	s_add_u32 s48, s48, 0x2000
	s_addc_u32 s49, s49, 0
	global_load_dwordx4 v[44:47], v26, s[48:49]
	global_load_dwordx4 v[48:51], v26, s[48:49] offset:16
	s_add_u32 s48, s48, 0x2000
	s_addc_u32 s49, s49, 0
	global_load_dwordx4 v[52:55], v26, s[48:49]
	global_load_dwordx4 v[56:59], v26, s[48:49] offset:16
	s_add_u32 s48, s48, 0x2000
	s_addc_u32 s49, s49, 0
	global_load_dwordx4 v[60:63], v26, s[48:49]
	global_load_dwordx4 v[64:67], v26, s[48:49] offset:16
	global_load_dwordx4 v[68:71], v26, s[50:51]
	global_load_dwordx4 v[72:75], v26, s[50:51] offset:16
	s_mov_b32 s3, s58

.LBB0_1864:
	s_or_b64 exec, exec, s[4:5]
	s_cmp_lt_i32 s61, 20
	s_cbranch_scc1 .LBB0_1918
	s_waitcnt vmcnt(0) lgkmcnt(0)
	s_barrier
	v_readfirstlane_b32 s2, v162
	s_lshl_b32 s3, s33, 8
	s_add_u32 s6, s84, s3
	s_addc_u32 s7, s85, 0
	s_cmp_lg_u32 s2, 0
	s_cbranch_scc1 .Lgb19_wait
	s_mov_b64 s[8:9], exec
	s_mov_b64 exec, 1
	v_mov_b32_e32 v0, 0x12000
	ds_read_b64 v[2:3], v0
	v_mov_b32_e32 v0, 0x1400
	v_mov_b32_e32 v1, 1
	global_atomic_add v4, v0, v1, s[6:7] sc0
	s_mov_b32 s13, 0
	s_waitcnt lgkmcnt(0)
	v_readfirstlane_b32 s10, v2
	v_readfirstlane_b32 s11, v3
	v_mov_b32_e32 v0, 0x3400
	s_nop 3
	s_mul_i32 s10, s10, 16
	s_mul_i32 s11, s11, 16
	s_waitcnt vmcnt(0)
	v_readfirstlane_b32 s12, v4
	s_nop 3
	s_add_u32 s12, s12, 1
	s_cmp_lg_u32 s12, s10
	s_cbranch_scc1 .Lgb19_poll
	buffer_wbl2 sc1
	s_waitcnt vmcnt(0)
	global_atomic_add v0, v1, s[84:85]

.Lgb19_wait:
	s_barrier
.LBB0_1918:
	s_cmp_gt_i32 s60, 20
	s_cselect_b64 s[2:3], -1, 0
	s_cmp_lt_i32 s61, 20
	s_cselect_b64 s[4:5], -1, 0
	s_or_b64 s[2:3], s[2:3], s[4:5]
	s_and_b64 vcc, exec, s[2:3]
	s_cbranch_vccnz .LBB0_2234
	v_lshlrev_b32_e32 v7, 3, v162
	s_waitcnt vmcnt(62)
	v_bfe_u32 v65, v162, 4, 2
	v_and_b32_e32 v64, 0x78, v7
	v_mov_b32_e32 v9, 0x11500
	s_mov_b64 s[62:63], s[0:1]
	v_lshlrev_b32_e32 v0, 1, v64
	v_lshl_or_b32 v111, v65, 5, v9
	v_mul_u32_u24_e32 v9, 0x88, v163
	s_load_dwordx2 s[64:65], s[62:63], 0xe0
	v_lshl_add_u32 v112, v9, 1, v0
	v_add_u32_e32 v9, 0x100, v162
	v_lshrrev_b32_e32 v114, 4, v9
	v_mul_u32_u24_e32 v10, 0x88, v114
	v_lshl_add_u32 v115, v10, 1, v0
	v_add_u32_e32 v10, 0x200, v162
	v_lshrrev_b32_e32 v117, 4, v10
	v_and_b32_e32 v1, 63, v162
	v_and_b32_e32 v68, 15, v162
	s_waitcnt lgkmcnt(0)
	s_add_u32 s66, s64, 0x1457d800
	v_lshlrev_b32_e32 v2, 4, v165
	v_mul_u32_u24_e32 v10, 0x88, v117
	s_addc_u32 s67, s65, 0
	v_lshl_or_b32 v67, v65, 2, v2
	v_lshlrev_b32_e32 v131, 2, v1
	v_lshl_add_u32 v118, v10, 1, v0
	v_add_u32_e32 v10, 0x300, v162
	v_cmp_eq_u32_e64 s[6:7], 0, v1
	v_cmp_gt_u32_e64 s[8:9], 2, v1
	v_cmp_gt_u32_e64 s[10:11], 4, v1
	v_cmp_gt_u32_e64 s[12:13], 8, v1
	v_cmp_gt_u32_e64 s[14:15], 16, v1
	v_cmp_gt_u32_e64 s[16:17], 32, v1
	v_mul_u32_u24_e32 v1, 0x88, v68
	v_mov_b32_e32 v73, 0
	v_or_b32_e32 v4, 16, v68
	v_or_b32_e32 v5, 32, v68
	v_or_b32_e32 v6, 48, v68
	v_lshrrev_b32_e32 v120, 4, v10
	v_lshl_add_u32 v124, v1, 1, v168
	v_mov_b32_e32 v1, 0x11400
	v_or_b32_e32 v14, 1, v67
	v_or_b32_e32 v15, 2, v67
	v_or_b32_e32 v16, 3, v67
	s_add_u32 s70, s64, 0x1037a100
	v_and_b32_e32 v66, 56, v7
	v_and_b32_e32 v109, 24, v7
	v_lshl_or_b32 v7, v65, 3, v169
	v_mul_u32_u24_e32 v10, 0x88, v120
	v_lshl_or_b32 v125, v68, 2, v1
	v_lshl_or_b32 v126, v4, 2, v1
	v_lshl_or_b32 v127, v5, 2, v1
	v_lshl_or_b32 v128, v6, 2, v1
	v_lshl_or_b32 v130, v67, 2, v1
	v_lshl_or_b32 v133, v14, 2, v1
	v_lshl_or_b32 v135, v15, 2, v1
	v_lshl_or_b32 v137, v16, 2, v1
	s_addc_u32 s71, s65, 0
	v_mov_b32_e32 v1, v73
	v_lshlrev_b32_e32 v3, 7, v67
	v_lshlrev_b32_e32 v8, 1, v68
	v_lshl_add_u32 v121, v10, 1, v0
	v_lshrrev_b32_e32 v145, 3, v162
	v_lshrrev_b32_e32 v123, 3, v9
	v_mul_u32_u24_e32 v129, 0x90, v7
	v_mul_u32_u24_e32 v11, 0x110, v7
	v_or_b32_e32 v7, 32, v7
	v_or_b32_e32 v2, v2, v68
	v_mul_u32_u24_e32 v17, 0x90, v67
	v_lshl_add_u64 v[96:97], s[70:71], 0, v[0:1]
	v_mbcnt_lo_u32_b32 v0, -1, 0
	s_mov_b64 s[54:55], src_shared_base
	v_or_b32_e32 v70, v3, v68
	v_lshlrev_b32_e32 v72, 1, v66
	v_lshl_or_b32 v110, v165, 5, v109
	v_mul_u32_u24_e32 v10, 0x90, v145
	v_mul_u32_u24_e32 v9, 0x90, v123
	v_mul_u32_u24_e32 v7, 0x90, v7
	v_mul_u32_u24_e32 v12, 0x110, v2
	v_mul_u32_u24_e32 v2, 0x90, v2
	v_mul_u32_u24_e32 v13, 0x110, v67
	v_or_b32_e32 v132, v17, v8
	s_add_u32 s2, s64, 0x1247a100
	v_mbcnt_hi_u32_b32 v155, -1, v0
	v_bfrev_b32_e32 v0, 0.5
	v_mov_b32_e32 v71, v73
	v_cmp_gt_u32_e64 s[4:5], 64, v162
	v_or_b32_e32 v69, 0x11400, v131
	v_or_b32_e32 v108, 0x11500, v131
	v_add_u32_e32 v113, 0x4400, v112
	v_add_u32_e32 v116, 0x4400, v115
	v_add_u32_e32 v119, 0x4400, v118
	v_add_u32_e32 v122, 0x4400, v121
	s_mov_b32 s69, 0
	v_cmp_le_u32_e64 s[18:19], v68, v67
	v_cmp_le_u32_e64 s[20:21], v4, v67
	v_cmp_le_u32_e64 s[22:23], v5, v67
	v_cmp_le_u32_e64 s[24:25], v6, v67
	v_cmp_le_u32_e64 s[26:27], v68, v14
	v_add_u32_e32 v134, 0x90, v132
	v_cmp_le_u32_e64 s[28:29], v4, v14
	v_cmp_le_u32_e64 s[30:31], v5, v14
	v_cmp_le_u32_e64 s[34:35], v6, v14
	v_cmp_le_u32_e64 s[36:37], v68, v15
	v_add_u32_e32 v136, 0x120, v132
	v_cmp_le_u32_e64 s[38:39], v4, v15
	v_cmp_le_u32_e64 s[40:41], v5, v15
	v_cmp_le_u32_e64 s[42:43], v6, v15
	v_cmp_le_u32_e64 s[44:45], v68, v16
	v_add_u32_e32 v138, 0x1b0, v132
	v_cmp_le_u32_e64 s[46:47], v4, v16
	v_cmp_le_u32_e64 s[48:49], v5, v16
	v_cmp_le_u32_e64 s[50:51], v6, v16
	v_lshl_or_b32 v74, v14, 7, v68
	v_mov_b32_e32 v75, v73
	v_lshl_or_b32 v76, v15, 7, v68
	v_mov_b32_e32 v77, v73
	v_lshl_or_b32 v78, v16, 7, v68
	v_mov_b32_e32 v79, v73
	s_addc_u32 s3, s65, 0
	v_lshl_add_u64 v[80:81], s[70:71], 0, v[72:73]
	v_or_b32_e32 v82, v3, v4
	v_mov_b32_e32 v83, v73
	s_waitcnt vmcnt(2)
	v_or_b32_e32 v84, v3, v5
	v_mov_b32_e32 v85, v73
	v_or_b32_e32 v86, v3, v6
	v_mov_b32_e32 v87, v73
	s_waitcnt vmcnt(1)
	v_or_b32_e32 v88, 64, v70
	v_mov_b32_e32 v89, v73
	v_or_b32_e32 v90, 0x50, v70
	v_mov_b32_e32 v91, v73
	s_waitcnt vmcnt(0)
	v_or_b32_e32 v92, 0x60, v70
	v_mov_b32_e32 v93, v73
	v_or_b32_e32 v94, 0x70, v70
	v_mov_b32_e32 v95, v73
	v_sub_u32_e32 v139, 0, v67
	v_not_b32_e32 v140, v123
	v_not_b32_e32 v141, v145
	v_not_b32_e32 v142, v120
	v_not_b32_e32 v143, v117
	v_not_b32_e32 v144, v114
	v_not_b32_e32 v146, v163
	v_mov_b32_e32 v98, 0x11ff0
	v_mov_b32_e32 v101, s55
	v_mov_b32_e32 v100, 0x11ff0
	s_mov_b32 s59, 0xab7a100
	v_add_u32_e32 v147, v72, v10
	v_add_u32_e32 v148, v72, v9
	v_add_u32_e32 v149, v8, v13
	v_add_u32_e32 v150, v168, v12
	v_mov_b32_e32 v151, 0x114fc
	v_add_u32_e32 v152, v168, v2
	v_add_u32_e32 v153, v109, v11
	v_add_u32_e32 v154, v110, v7
	s_mov_b32 s74, 0x6000000
	v_lshlrev_b32_e32 v72, 1, v68
	v_lshl_or_b32 v156, v155, 2, v0
	s_branch .LBB0_1922

.LBB0_2180:
	s_cmp_lt_i32 s61, 21
	s_cbranch_scc1 .LBB0_2234
	s_waitcnt vmcnt(0) lgkmcnt(0)
	s_barrier
	v_readfirstlane_b32 s2, v162
	s_lshl_b32 s3, s33, 8
	s_add_u32 s6, s84, s3
	s_addc_u32 s7, s85, 0
	s_cmp_lg_u32 s2, 0
	s_cbranch_scc1 .Lgb20_wait
	s_mov_b64 s[8:9], exec
	s_mov_b64 exec, 1
	v_mov_b32_e32 v0, 0x12000
	ds_read_b64 v[2:3], v0
	v_mov_b32_e32 v0, 0x1400
	v_mov_b32_e32 v1, 1
	global_atomic_add v4, v0, v1, s[6:7] sc0
	s_mov_b32 s13, 0
	s_waitcnt lgkmcnt(0)
	v_readfirstlane_b32 s10, v2
	v_readfirstlane_b32 s11, v3
	v_mov_b32_e32 v0, 0x3400
	s_nop 3
	s_mul_i32 s10, s10, 17
	s_mul_i32 s11, s11, 17
	s_waitcnt vmcnt(0)
	v_readfirstlane_b32 s12, v4
	s_nop 3
	s_add_u32 s12, s12, 1
	s_cmp_lg_u32 s12, s10
	s_cbranch_scc1 .Lgb20_poll
	buffer_wbl2 sc1
	s_waitcnt vmcnt(0)
	global_atomic_add v0, v1, s[84:85]

.Lgb20_wait:
	s_barrier
.LBB0_2234:
	s_cmp_gt_i32 s60, 21
	s_cselect_b64 s[2:3], -1, 0
	s_cmp_lt_i32 s61, 21
	s_cselect_b64 s[4:5], -1, 0
	s_or_b64 s[2:3], s[2:3], s[4:5]
	s_and_b64 vcc, exec, s[2:3]
	s_cbranch_vccnz .LBB0_2292
	v_and_b32_e32 v0, 30, v167
	v_lshl_add_u32 v8, s58, 3, v0
	s_movk_i32 s2, 0x2000
	s_mov_b64 s[4:5], s[0:1]
	v_cmp_gt_i32_e32 vcc, s2, v8
	s_and_saveexec_b64 s[6:7], vcc
	s_cbranch_execz .LBB0_2238
	v_lshlrev_b32_e32 v0, 3, v162
	s_load_dwordx4 s[12:15], s[4:5], 0x88
	s_load_dwordx2 s[2:3], s[4:5], 0xe0
	s_load_dword s8, s[0:1], 0xf0
	v_and_b32_e32 v0, 0x1f8, v0
	v_mbcnt_lo_u32_b32 v1, -1, 0
	v_mbcnt_hi_u32_b32 v1, -1, v1
	v_or_b32_e32 v3, 0x200, v0
	v_lshrrev_b32_e32 v4, 1, v162
	v_and_b32_e32 v2, 64, v1
	v_and_b32_e32 v10, 28, v4
	v_mov_b32_e32 v11, 0
	v_lshrrev_b32_e32 v4, 4, v3
	v_add_u32_e32 v2, 64, v2
	s_waitcnt lgkmcnt(0)
	v_lshl_add_u64 v[12:13], s[12:13], 0, v[10:11]
	v_and_b32_e32 v10, 60, v4
	v_xor_b32_e32 v4, 32, v1
	v_cmp_lt_i32_e32 vcc, v4, v2
	s_add_u32 s4, s14, 0x1000
	s_addc_u32 s5, s15, 0
	v_cndmask_b32_e32 v4, v1, v4, vcc
	v_lshlrev_b32_e32 v25, 2, v4
	v_xor_b32_e32 v4, 16, v1
	v_cmp_lt_i32_e32 vcc, v4, v2
	v_lshl_add_u64 v[14:15], s[12:13], 0, v[10:11]
	v_lshlrev_b32_e32 v10, 2, v0
	v_cndmask_b32_e32 v4, v1, v4, vcc
	v_lshlrev_b32_e32 v29, 2, v4
	v_xor_b32_e32 v4, 8, v1
	v_cmp_lt_i32_e32 vcc, v4, v2
	v_lshl_add_u64 v[16:17], s[4:5], 0, v[10:11]
	v_lshlrev_b32_e32 v10, 2, v3
	v_cndmask_b32_e32 v4, v1, v4, vcc
	v_lshlrev_b32_e32 v31, 2, v4
	v_xor_b32_e32 v4, 4, v1
	v_cmp_lt_i32_e32 vcc, v4, v2
	v_and_b32_e32 v0, 63, v162
	v_ashrrev_i32_e32 v9, 31, v8
	v_cndmask_b32_e32 v4, v1, v4, vcc
	v_lshlrev_b32_e32 v38, 2, v4
	v_xor_b32_e32 v4, 2, v1
	v_cmp_lt_i32_e32 vcc, v4, v2
	s_lshl_b32 s8, s8, 3
	v_lshl_add_u64 v[18:19], s[4:5], 0, v[10:11]
	v_cndmask_b32_e32 v4, v1, v4, vcc
	v_lshlrev_b32_e32 v39, 2, v4
	v_xor_b32_e32 v4, 1, v1
	v_cmp_lt_i32_e32 vcc, v4, v2
	v_lshlrev_b32_e32 v10, 4, v0
	s_ashr_i32 s9, s8, 31
	v_cndmask_b32_e32 v1, v1, v4, vcc
	v_lshlrev_b32_e32 v40, 2, v1
	v_lshlrev_b64 v[0:1], 12, v[8:9]
	v_lshl_add_u64 v[20:21], s[2:3], 0, v[0:1]
	v_lshlrev_b64 v[0:1], 11, v[8:9]
	s_lshl_b64 s[10:11], s[8:9], 12
	v_lshl_add_u64 v[22:23], s[2:3], 0, v[0:1]
	s_lshl_b64 s[12:13], s[8:9], 11
	s_mov_b64 s[14:15], 0
	s_mov_b32 s2, 0x1037b000
	s_mov_b32 s16, 0x3a800000
	v_mov_b32_e32 v24, 0x358637bd
	s_mov_b32 s3, 0x800000
	s_mov_b32 s9, 0x1257a000
	s_mov_b32 s17, 0x1257b000
	s_movk_i32 s18, 0x1fff

.LBB0_2238:
	s_or_b64 exec, exec, s[6:7]
	s_cmp_lt_u32 s61, 22
	s_cbranch_scc1 .LBB0_2292
	s_waitcnt vmcnt(0) lgkmcnt(0)
	s_barrier
	v_readfirstlane_b32 s2, v162
	s_lshl_b32 s3, s33, 8
	s_add_u32 s6, s84, s3
	s_addc_u32 s7, s85, 0
	s_cmp_lg_u32 s2, 0
	s_cbranch_scc1 .Lgb21_wait
	s_mov_b64 s[8:9], exec
	s_mov_b64 exec, 1
	v_mov_b32_e32 v0, 0x12000
	ds_read_b64 v[2:3], v0
	v_mov_b32_e32 v0, 0x1400
	v_mov_b32_e32 v1, 1
	global_atomic_add v4, v0, v1, s[6:7] sc0
	s_mov_b32 s13, 0
	s_waitcnt lgkmcnt(0)
	v_readfirstlane_b32 s10, v2
	v_readfirstlane_b32 s11, v3
	v_mov_b32_e32 v0, 0x3400
	s_nop 3
	s_mul_i32 s10, s10, 18
	s_mul_i32 s11, s11, 18
	s_waitcnt vmcnt(0)
	v_readfirstlane_b32 s12, v4
	s_nop 3
	s_add_u32 s12, s12, 1
	s_cmp_lg_u32 s12, s10
	s_cbranch_scc1 .Lgb21_poll
	buffer_wbl2 sc1
	s_waitcnt vmcnt(0)
	global_atomic_add v0, v1, s[84:85]

.Lgb21_wait:
	s_barrier
.LBB0_2292:
	s_cmp_gt_i32 s60, 22
	s_cselect_b64 s[2:3], -1, 0
	s_cmp_lt_i32 s61, 22
	s_cselect_b64 s[4:5], -1, 0
	s_or_b64 s[2:3], s[2:3], s[4:5]
	s_and_b64 vcc, exec, s[2:3]
	s_cbranch_vccnz .LBB0_2352
	s_load_dwordx2 s[4:5], s[0:1], 0xe0
	s_load_dword s16, s[0:1], 0xf0
	v_and_b32_e32 v240, 63, v162
	v_lshrrev_b32_e32 v247, 6, v162
	v_lshrrev_b32_e32 v242, 3, v240
	v_lshl_add_u32 v242, v247, 5, v242
	v_and_b32_e32 v243, 7, v240
	v_lshrrev_b32_e32 v244, 4, v240
	v_xor_b32_e32 v243, v243, v244
	v_lshlrev_b32_e32 v243, 4, v243
	v_mov_b32_e32 v241, 0x1000
	v_mad_u32_u24 v248, v242, v241, v243
	v_xor_b32_e32 v249, 64, v248
	v_add_u32_e32 v249, 0x8000, v249
	v_add_u32_e32 v250, 0x10000, v248
	v_xor_b32_e32 v251, 64, v248
	v_add_u32_e32 v251, 0x18000, v251
	v_and_b32_e32 v241, 15, v240
	v_lshrrev_b32_e32 v242, 1, v241
	v_xor_b32_e32 v242, v242, v244
	v_lshlrev_b32_e32 v242, 4, v242
	v_lshl_or_b32 v242, v241, 7, v242
	v_lshrrev_b32_e32 v243, 1, v247
	v_lshl_or_b32 v252, v243, 13, v242
	v_xor_b32_e32 v253, 64, v252
	v_and_b32_e32 v243, 1, v247
	v_lshl_or_b32 v254, v243, 13, v242
	v_xor_b32_e32 v255, 64, v254
	v_and_b32_e32 v240, 63, v162
	v_and_b32_e32 v241, 15, v240
	v_lshrrev_b32_e32 v242, 4, v240
	v_lshrrev_b32_e32 v243, 1, v247
	v_and_b32_e32 v244, 1, v247
	v_lshl_or_b32 v245, v244, 6, v241
	v_lshlrev_b32_e32 v243, 4, v243
	v_add_u32_e32 v243, v243, v242
	v_lshl_add_u32 v246, v243, 12, v245
	v_lshlrev_b32_e32 v246, 2, v246
	v_lshlrev_b32_e32 v245, 2, v245
	s_waitcnt lgkmcnt(0)
	s_add_u32 s26, s4, 0x1257a100
	s_addc_u32 s27, s5, 0
	s_add_u32 s28, s4, 0x1c80000
	s_addc_u32 s29, s5, 0
	s_mov_b32 s15, s58

.LBB0_2356:
	s_or_b64 exec, exec, s[10:11]
	s_cmp_lt_u32 s61, 24
	s_cbranch_scc1 .LBB0_2410
	s_waitcnt vmcnt(0) lgkmcnt(0)
	s_barrier
	v_readfirstlane_b32 s2, v162
	s_lshl_b32 s3, s33, 8
	s_add_u32 s6, s84, s3
	s_addc_u32 s7, s85, 0
	s_cmp_lg_u32 s2, 0
	s_cbranch_scc1 .Lgb23_wait
	s_mov_b64 s[8:9], exec
	s_mov_b64 exec, 1
	v_mov_b32_e32 v0, 0x12000
	ds_read_b64 v[2:3], v0
	v_mov_b32_e32 v0, 0x1400
	v_mov_b32_e32 v1, 1
	global_atomic_add v4, v0, v1, s[6:7] sc0
	s_mov_b32 s13, 0
	s_waitcnt lgkmcnt(0)
	v_readfirstlane_b32 s10, v2
	v_readfirstlane_b32 s11, v3
	v_mov_b32_e32 v0, 0x3400
	s_nop 3
	s_mul_i32 s10, s10, 19
	s_mul_i32 s11, s11, 19
	s_waitcnt vmcnt(0)
	v_readfirstlane_b32 s12, v4
	s_nop 3
	s_add_u32 s12, s12, 1
	s_cmp_lg_u32 s12, s10
	s_cbranch_scc1 .Lgb23_poll
	buffer_wbl2 sc1
	s_waitcnt vmcnt(0)
	global_atomic_add v0, v1, s[84:85]

.Lgb23_wait:
	s_barrier
.LBB0_2410:
	s_cmp_gt_i32 s60, 24
	s_cselect_b64 s[2:3], -1, 0
	s_cmp_lt_i32 s61, 24
	s_cselect_b64 s[4:5], -1, 0
	s_or_b64 s[2:3], s[2:3], s[4:5]
	s_and_b64 vcc, exec, s[2:3]
	s_cbranch_vccnz .LBB0_2474
	s_load_dwordx2 s[4:5], s[0:1], 0xe0
	s_load_dword s16, s[0:1], 0xf0
	v_and_b32_e32 v240, 63, v162
	v_lshrrev_b32_e32 v247, 6, v162
	v_lshrrev_b32_e32 v242, 3, v240
	v_lshl_add_u32 v242, v247, 5, v242
	v_and_b32_e32 v243, 7, v240
	v_lshrrev_b32_e32 v244, 4, v240
	v_xor_b32_e32 v243, v243, v244
	v_lshlrev_b32_e32 v243, 4, v243
	v_mov_b32_e32 v241, 0x800
	v_mad_u32_u24 v248, v242, v241, v243
	v_xor_b32_e32 v249, 64, v248
	v_add_u32_e32 v249, 0x4000, v249
	v_add_u32_e32 v250, 0x8000, v248
	v_xor_b32_e32 v251, 64, v248
	v_add_u32_e32 v251, 0xc000, v251
	v_and_b32_e32 v241, 15, v240
	v_lshrrev_b32_e32 v242, 1, v241
	v_xor_b32_e32 v242, v242, v244
	v_lshlrev_b32_e32 v242, 4, v242
	v_lshl_or_b32 v242, v241, 7, v242
	v_lshrrev_b32_e32 v243, 1, v247
	v_lshl_or_b32 v252, v243, 13, v242
	v_xor_b32_e32 v253, 64, v252
	v_and_b32_e32 v243, 1, v247
	v_lshl_or_b32 v254, v243, 13, v242
	v_xor_b32_e32 v255, 64, v254
	v_and_b32_e32 v240, 63, v162
	v_and_b32_e32 v241, 15, v240
	v_lshrrev_b32_e32 v242, 4, v240
	v_mul_u32_u24_e32 v245, 0x1400, v247
	v_mul_u32_u24_e32 v243, 80, v241
	v_add_u32_e32 v243, v243, v245
	v_lshl_add_u32 v244, v242, 3, v243
	v_lshrrev_b32_e32 v243, 2, v240
	v_mul_u32_u24_e32 v246, 80, v243
	v_add_u32_e32 v246, v246, v245
	v_and_b32_e32 v241, 3, v240
	v_lshl_add_u32 v246, v241, 4, v246
	v_mov_b32_e32 v245, v244
	v_lshrrev_b32_e32 v242, 1, v247
	v_lshl_add_u32 v243, v242, 6, v243
	v_mov_b32_e32 v242, 0x1600
	v_mul_u32_u24_e32 v243, v243, v242
	v_and_b32_e32 v242, 1, v247
	v_lshl_add_u32 v243, v242, 6, v243
	v_lshl_add_u32 v239, v241, 4, v243
	s_waitcnt lgkmcnt(0)
	s_add_u32 s26, s4, 0x8b7a100
	s_addc_u32 s27, s5, 0
	s_add_u32 s28, s4, 0x3a80000
	s_addc_u32 s29, s5, 0
	s_mov_b32 s15, s58

.Lf24_end:
.LBB0_2420:
	s_cmp_lt_i32 s61, 25
	s_cbranch_scc1 .LBB0_2474
	s_waitcnt vmcnt(0) lgkmcnt(0)
	s_barrier
	v_readfirstlane_b32 s2, v162
	s_lshl_b32 s3, s33, 8
	s_add_u32 s6, s84, s3
	s_addc_u32 s7, s85, 0
	s_cmp_lg_u32 s2, 0
	s_cbranch_scc1 .Lgb24_wait
	s_mov_b64 s[8:9], exec
	s_mov_b64 exec, 1
	v_mov_b32_e32 v0, 0x12000
	ds_read_b64 v[2:3], v0
	v_mov_b32_e32 v0, 0x1400
	v_mov_b32_e32 v1, 1
	global_atomic_add v4, v0, v1, s[6:7] sc0
	s_mov_b32 s13, 0
	s_waitcnt lgkmcnt(0)
	v_readfirstlane_b32 s10, v2
	v_readfirstlane_b32 s11, v3
	v_mov_b32_e32 v0, 0x3400
	s_nop 3
	s_mul_i32 s10, s10, 20
	s_mul_i32 s11, s11, 20
	s_waitcnt vmcnt(0)
	v_readfirstlane_b32 s12, v4
	s_nop 3
	s_add_u32 s12, s12, 1
	s_cmp_lg_u32 s12, s10
	s_cbranch_scc1 .Lgb24_poll
	buffer_wbl2 sc1
	s_waitcnt vmcnt(0)
	global_atomic_add v0, v1, s[84:85]

.Lgb24_wait:
	s_barrier
.LBB0_2474:
	s_cmp_gt_i32 s60, 25
	s_cselect_b64 s[2:3], -1, 0
	s_cmp_lt_i32 s61, 25
	s_cselect_b64 s[4:5], -1, 0
	s_or_b64 s[2:3], s[2:3], s[4:5]
	s_and_b64 vcc, exec, s[2:3]
	s_cbranch_vccnz .LBB0_2534
	s_load_dwordx2 s[4:5], s[0:1], 0xe0
	s_load_dword s16, s[0:1], 0xf0
	v_and_b32_e32 v240, 63, v162
	v_lshrrev_b32_e32 v247, 6, v162
	v_lshrrev_b32_e32 v242, 3, v240
	v_lshl_add_u32 v242, v247, 5, v242
	v_and_b32_e32 v243, 7, v240
	v_lshrrev_b32_e32 v244, 4, v240
	v_xor_b32_e32 v243, v243, v244
	v_lshlrev_b32_e32 v243, 4, v243
	v_mov_b32_e32 v241, 0x1600
	v_mad_u32_u24 v248, v242, v241, v243
	v_xor_b32_e32 v249, 64, v248
	v_add_u32_e32 v249, 0xb000, v249
	v_add_u32_e32 v250, 0x16000, v248
	v_xor_b32_e32 v251, 64, v248
	v_add_u32_e32 v251, 0x21000, v251
	v_and_b32_e32 v241, 15, v240
	v_lshrrev_b32_e32 v242, 1, v241
	v_xor_b32_e32 v242, v242, v244
	v_lshlrev_b32_e32 v242, 4, v242
	v_lshl_or_b32 v242, v241, 7, v242
	v_lshrrev_b32_e32 v243, 1, v247
	v_lshl_or_b32 v252, v243, 13, v242
	v_xor_b32_e32 v253, 64, v252
	v_and_b32_e32 v243, 1, v247
	v_lshl_or_b32 v254, v243, 13, v242
	v_xor_b32_e32 v255, 64, v254
	v_and_b32_e32 v240, 63, v162
	v_and_b32_e32 v241, 15, v240
	v_lshrrev_b32_e32 v242, 4, v240
	v_lshrrev_b32_e32 v243, 1, v247
	v_and_b32_e32 v244, 1, v247
	v_lshl_or_b32 v245, v244, 6, v241
	v_lshlrev_b32_e32 v243, 4, v243
	v_add_u32_e32 v243, v243, v242
	v_lshl_add_u32 v246, v243, 12, v245
	v_lshlrev_b32_e32 v246, 2, v246
	v_lshlrev_b32_e32 v245, 2, v245
	s_waitcnt lgkmcnt(0)
	s_add_u32 s26, s4, 0x9b7a100
	s_addc_u32 s27, s5, 0
	s_add_u32 s28, s4, 0x5b80000
	s_addc_u32 s29, s5, 0
	s_mov_b32 s15, s58

.LBB0_2538:
	s_or_b64 exec, exec, s[10:11]
	s_cmp_lt_u32 s61, 27
	s_cbranch_scc1 .LBB0_2592
	s_waitcnt vmcnt(0) lgkmcnt(0)
	s_barrier
	v_readfirstlane_b32 s2, v162
	s_lshl_b32 s3, s33, 8
	s_add_u32 s6, s84, s3
	s_addc_u32 s7, s85, 0
	s_cmp_lg_u32 s2, 0
	s_cbranch_scc1 .Lgb26_wait
	s_mov_b64 s[8:9], exec
	s_mov_b64 exec, 1
	v_mov_b32_e32 v0, 0x12000
	ds_read_b64 v[2:3], v0
	v_mov_b32_e32 v0, 0x1400
	v_mov_b32_e32 v1, 1
	global_atomic_add v4, v0, v1, s[6:7] sc0
	s_mov_b32 s13, 0
	s_waitcnt lgkmcnt(0)
	v_readfirstlane_b32 s10, v2
	v_readfirstlane_b32 s11, v3
	v_mov_b32_e32 v0, 0x3400
	s_nop 3
	s_mul_i32 s10, s10, 21
	s_mul_i32 s11, s11, 21
	s_waitcnt vmcnt(0)
	v_readfirstlane_b32 s12, v4
	s_nop 3
	s_add_u32 s12, s12, 1
	s_cmp_lg_u32 s12, s10
	s_cbranch_scc1 .Lgb26_poll
	buffer_wbl2 sc1
	s_waitcnt vmcnt(0)
	global_atomic_add v0, v1, s[84:85]

.Lgb26_wait:
	s_barrier
.LBB0_2592:
	s_cmp_gt_i32 s60, 27
	s_cselect_b64 s[2:3], -1, 0
	s_cmp_lt_i32 s61, 27
	s_cselect_b64 s[4:5], -1, 0
	s_or_b64 s[2:3], s[2:3], s[4:5]
	s_and_b64 vcc, exec, s[2:3]
	s_cbranch_vccnz .LBB0_2655
	s_mov_b64 s[4:5], s[0:1]
	s_cmpk_gt_i32 s58, 0x3ff
	s_cbranch_scc1 .LBB0_2601
	s_load_dwordx2 s[4:5], s[4:5], 0xe0
	v_lshrrev_b32_e32 v10, 3, v162
	v_lshlrev_b32_e32 v0, 3, v162
	v_mov_b32_e32 v1, 0
	v_and_b32_e32 v4, 56, v0
	v_lshlrev_b32_e32 v2, 9, v10
	v_mov_b32_e32 v3, v1
	v_xor_b32_e32 v11, v163, v162
	s_waitcnt lgkmcnt(0)
	v_lshl_add_u64 v[2:3], s[4:5], 0, v[2:3]
	v_lshlrev_b32_e32 v6, 1, v4
	v_mov_b32_e32 v7, v1
	v_lshl_add_u64 v[2:3], v[2:3], 0, v[6:7]
	v_lshlrev_b32_e32 v7, 4, v11
	v_and_b32_e32 v9, 15, v162
	s_add_u32 s2, s4, 0x8b7a100
	v_bfe_u32 v6, v162, 1, 3
	v_and_b32_e32 v7, 0x70, v7
	s_load_dword s10, s[0:1], 0xf0
	v_bfe_u32 v5, v162, 6, 1
	v_lshrrev_b32_e32 v8, 7, v162
	s_addc_u32 s3, s5, 0
	v_lshlrev_b32_e32 v0, 11, v10
	v_bitop3_b32 v6, v163, v6, 3 bitop3:0x6c
	v_lshl_or_b32 v10, v10, 7, v7
	v_lshlrev_b32_e32 v7, 7, v9
	v_lshl_or_b32 v13, v8, 13, v7
	v_lshl_or_b32 v7, v5, 13, v7
	v_lshlrev_b32_e32 v6, 4, v6
	s_add_u32 s11, s4, 0xbb7a100
	v_bfe_u32 v15, v162, 4, 2
	v_or_b32_e32 v11, v13, v6
	v_or_b32_e32 v12, v7, v6
	v_xor_b32_e32 v6, 64, v6
	s_addc_u32 s12, s5, 0
	s_mov_b64 s[6:7], 0x6ac0000
	v_or_b32_e32 v13, v13, v6
	v_or_b32_e32 v14, v7, v6
	v_lshlrev_b32_e32 v6, 6, v8
	v_lshlrev_b32_e32 v8, 2, v15
	s_add_u32 s13, s4, 0xab7a100
	v_lshl_add_u64 v[2:3], v[2:3], 0, s[6:7]
	s_addc_u32 s14, s5, 0
	v_lshl_or_b32 v15, v5, 6, v9
	s_lshl_b32 s15, s58, 1
	s_waitcnt lgkmcnt(0)
	s_lshl_b32 s16, s10, 1
	s_lshl_b32 s17, s58, 7
	s_lshl_b32 s18, s10, 7
	s_mov_b32 s5, 0
	v_lshlrev_b32_e32 v4, 1, v4
	v_mov_b32_e32 v5, v1
	s_mov_b32 s19, 0x10000
	s_mov_b32 s20, 0x20000
	s_mov_b32 s21, 0x30000
	s_movk_i32 s22, 0x4000
	s_mov_b32 s23, 0x8000
	s_mov_b32 s24, 0xc000
	v_lshlrev_b32_e32 v6, 1, v6
	v_mov_b32_e32 v7, v1
	v_lshlrev_b32_e32 v8, 1, v8
	v_mov_b32_e32 v9, v1
	s_mov_b32 s25, s58
	s_branch .LBB0_2597

.LBB0_2601:
	s_cmp_lt_i32 s61, 28
	s_cbranch_scc1 .LBB0_2655
	s_waitcnt vmcnt(0) lgkmcnt(0)
	s_barrier
	v_readfirstlane_b32 s2, v162
	s_lshl_b32 s3, s33, 8
	s_add_u32 s6, s84, s3
	s_addc_u32 s7, s85, 0
	s_cmp_lg_u32 s2, 0
	s_cbranch_scc1 .Lgb27_wait
	s_mov_b64 s[8:9], exec
	s_mov_b64 exec, 1
	v_mov_b32_e32 v0, 0x12000
	ds_read_b64 v[2:3], v0
	v_mov_b32_e32 v0, 0x1400
	v_mov_b32_e32 v1, 1
	global_atomic_add v4, v0, v1, s[6:7] sc0
	s_mov_b32 s13, 0
	s_waitcnt lgkmcnt(0)
	v_readfirstlane_b32 s10, v2
	v_readfirstlane_b32 s11, v3
	v_mov_b32_e32 v0, 0x3400
	s_nop 3
	s_mul_i32 s10, s10, 22
	s_mul_i32 s11, s11, 22
	s_waitcnt vmcnt(0)
	v_readfirstlane_b32 s12, v4
	s_nop 3
	s_add_u32 s12, s12, 1
	s_cmp_lg_u32 s12, s10
	s_cbranch_scc1 .Lgb27_poll
	buffer_wbl2 sc1
	s_waitcnt vmcnt(0)
	global_atomic_add v0, v1, s[84:85]

.Lgb27_wait:
	s_barrier
.LBB0_2655:
	s_cmp_gt_i32 s60, 28
	s_cselect_b64 s[2:3], -1, 0
	s_cmp_lt_i32 s61, 28
	s_cselect_b64 s[4:5], -1, 0
	s_or_b64 s[2:3], s[2:3], s[4:5]
	s_and_b64 vcc, exec, s[2:3]
	s_cbranch_vccnz .LBB0_2719
	s_mov_b64 s[4:5], s[0:1]
	s_cmpk_gt_i32 s58, 0x1ff
	s_cbranch_scc1 .LBB0_2665
	s_load_dwordx2 s[4:5], s[4:5], 0xe0
	v_xor_b32_e32 v5, v163, v162
	v_lshlrev_b32_e32 v5, 4, v5
	v_and_b32_e32 v3, 15, v162
	v_lshrrev_b32_e32 v134, 3, v162
	v_and_b32_e32 v5, 0x70, v5
	v_lshrrev_b32_e32 v2, 7, v162
	v_lshl_or_b32 v135, v134, 7, v5
	v_lshlrev_b32_e32 v5, 7, v3
	v_bfe_u32 v4, v162, 4, 2
	v_mov_b32_e32 v97, 0
	v_lshl_or_b32 v7, v2, 13, v5
	v_lshlrev_b32_e32 v2, 6, v2
	v_lshlrev_b32_e32 v96, 1, v3
	v_lshl_or_b32 v140, v4, 2, v2
	s_waitcnt lgkmcnt(0)
	v_lshl_add_u64 v[2:3], s[4:5], 0, v[96:97]
	s_mov_b64 s[2:3], 0x9b7a100
	v_lshl_add_u64 v[98:99], v[2:3], 0, s[2:3]
	s_add_u32 s3, s4, 0x6a80000
	s_addc_u32 s44, s5, 0
	s_add_u32 s45, s4, 0xab7a100
	v_bfe_u32 v6, v162, 1, 3
	s_load_dword s2, s[0:1], 0xf0
	s_addc_u32 s46, s5, 0
	v_bfe_u32 v1, v162, 6, 1
	v_bitop3_b32 v6, v163, v6, 3 bitop3:0x6c
	s_add_u32 s47, s4, 0x6680000
	v_lshlrev_b32_e32 v0, 3, v162
	v_lshl_or_b32 v5, v1, 13, v5
	v_lshlrev_b32_e32 v6, 4, v6
	s_addc_u32 s48, s5, 0
	v_and_b32_e32 v0, 56, v0
	v_or_b32_e32 v136, v7, v6
	v_or_b32_e32 v137, v5, v6
	v_xor_b32_e32 v6, 64, v6
	v_lshlrev_b32_e32 v1, 6, v1
	s_add_u32 s49, s4, 0xbb7a100
	v_or_b32_e32 v138, v7, v6
	v_or_b32_e32 v139, v5, v6
	s_addc_u32 s50, s5, 0
	s_mov_b32 s5, 0
	v_lshlrev_b32_e32 v100, 1, v0
	v_mov_b32_e32 v101, v97
	s_mov_b64 s[6:7], 0x100
	v_lshlrev_b32_e32 v141, 1, v1
	s_mov_b64 s[8:9], 0x1000
	s_mov_b64 s[10:11], 0x1800
	s_mov_b64 s[12:13], 0x8000
	s_mov_b32 s51, 0x8000
	s_mov_b64 s[14:15], 0x8800
	s_mov_b64 s[16:17], 0x9000
	s_mov_b32 s54, 0x9000
	s_mov_b64 s[18:19], 0x9800
	s_mov_b64 s[20:21], 0x10000
	s_mov_b32 s55, 0x10000
	s_mov_b64 s[22:23], 0x10800
	s_mov_b64 s[24:25], 0x11000
	s_mov_b32 s59, 0x11000
	s_mov_b64 s[26:27], 0x11800
	s_mov_b64 s[28:29], 0x18000
	s_mov_b32 s62, 0x18000
	s_mov_b64 s[30:31], 0x18800
	s_mov_b64 s[34:35], 0x19000
	s_mov_b32 s63, 0x19000
	s_mov_b64 s[36:37], 0x19800
	s_mov_b32 s64, s58

.LBB0_2665:
	s_cmp_lt_i32 s61, 29
	s_cbranch_scc1 .LBB0_2719
	s_waitcnt vmcnt(0) lgkmcnt(0)
	s_barrier
	v_readfirstlane_b32 s2, v162
	s_lshl_b32 s3, s33, 8
	s_add_u32 s6, s84, s3
	s_addc_u32 s7, s85, 0
	s_cmp_lg_u32 s2, 0
	s_cbranch_scc1 .Lgb28_wait
	s_mov_b64 s[8:9], exec
	s_mov_b64 exec, 1
	v_mov_b32_e32 v0, 0x12000
	ds_read_b64 v[2:3], v0
	v_mov_b32_e32 v0, 0x1400
	v_mov_b32_e32 v1, 1
	global_atomic_add v4, v0, v1, s[6:7] sc0
	s_mov_b32 s13, 0
	s_waitcnt lgkmcnt(0)
	v_readfirstlane_b32 s10, v2
	v_readfirstlane_b32 s11, v3
	v_mov_b32_e32 v0, 0x3400
	s_nop 3
	s_mul_i32 s10, s10, 23
	s_mul_i32 s11, s11, 23
	s_waitcnt vmcnt(0)
	v_readfirstlane_b32 s12, v4
	s_nop 3
	s_add_u32 s12, s12, 1
	s_cmp_lg_u32 s12, s10
	s_cbranch_scc1 .Lgb28_poll
	buffer_wbl2 sc1
	s_waitcnt vmcnt(0)
	global_atomic_add v0, v1, s[84:85]

.Lgb28_wait:
	s_barrier
.LBB0_2719:
	s_cmp_gt_i32 s60, 29
	s_cselect_b64 s[2:3], -1, 0
	s_cmp_lt_i32 s61, 29
	s_cselect_b64 s[4:5], -1, 0
	s_or_b64 s[2:3], s[2:3], s[4:5]
	s_and_b64 vcc, exec, s[2:3]
	s_cbranch_vccnz .LBB0_2787
	s_load_dwordx2 s[4:5], s[0:1], 0xe0
	s_load_dword s16, s[0:1], 0xf0
	s_load_dwordx2 s[24:25], s[0:1], 0xb8
	v_and_b32_e32 v240, 63, v162
	v_lshrrev_b32_e32 v247, 6, v162
	v_lshrrev_b32_e32 v242, 3, v240
	v_lshl_add_u32 v242, v247, 5, v242
	v_and_b32_e32 v243, 7, v240
	v_lshrrev_b32_e32 v244, 4, v240
	v_xor_b32_e32 v243, v243, v244
	v_lshlrev_b32_e32 v243, 4, v243
	v_mov_b32_e32 v241, 0x800
	v_mad_u32_u24 v248, v242, v241, v243
	v_xor_b32_e32 v249, 64, v248
	v_add_u32_e32 v249, 0x4000, v249
	v_add_u32_e32 v250, 0x8000, v248
	v_xor_b32_e32 v251, 64, v248
	v_add_u32_e32 v251, 0xc000, v251
	v_and_b32_e32 v241, 15, v240
	v_lshrrev_b32_e32 v242, 1, v241
	v_xor_b32_e32 v242, v242, v244
	v_lshlrev_b32_e32 v242, 4, v242
	v_lshl_or_b32 v242, v241, 7, v242
	v_lshrrev_b32_e32 v243, 1, v247
	v_lshl_or_b32 v252, v243, 13, v242
	v_xor_b32_e32 v253, 64, v252
	v_and_b32_e32 v243, 1, v247
	v_lshl_or_b32 v254, v243, 13, v242
	v_xor_b32_e32 v255, 64, v254
	v_and_b32_e32 v240, 63, v162
	v_and_b32_e32 v241, 15, v240
	v_lshrrev_b32_e32 v242, 4, v240
	v_lshrrev_b32_e32 v243, 1, v247
	v_and_b32_e32 v244, 1, v247
	v_lshl_or_b32 v245, v244, 6, v241
	v_lshlrev_b32_e32 v243, 4, v243
	v_add_u32_e32 v243, v243, v242
	v_lshl_add_u32 v246, v243, 12, v245
	v_lshlrev_b32_e32 v246, 2, v246
	v_lshlrev_b32_e32 v245, 2, v245
	s_waitcnt lgkmcnt(0)
	s_add_u32 s26, s4, 0x9b7a100
	s_addc_u32 s27, s5, 0
	s_add_u32 s28, s4, 0x2280000
	s_addc_u32 s29, s5, 0
	s_mov_b32 s15, s58

.LBB0_2791:
	s_or_b64 exec, exec, s[10:11]
	s_cmp_lt_u32 s61, 31
	s_cbranch_scc1 .LBB0_2845
	s_waitcnt vmcnt(0) lgkmcnt(0)
	s_barrier
	v_readfirstlane_b32 s2, v162
	s_lshl_b32 s3, s33, 8
	s_add_u32 s6, s84, s3
	s_addc_u32 s7, s85, 0
	s_cmp_lg_u32 s2, 0
	s_cbranch_scc1 .Lgb30_wait
	s_mov_b64 s[8:9], exec
	s_mov_b64 exec, 1
	v_mov_b32_e32 v0, 0x12000
	ds_read_b64 v[2:3], v0
	v_mov_b32_e32 v0, 0x1400
	v_mov_b32_e32 v1, 1
	global_atomic_add v4, v0, v1, s[6:7] sc0
	s_mov_b32 s13, 0
	s_waitcnt lgkmcnt(0)
	v_readfirstlane_b32 s10, v2
	v_readfirstlane_b32 s11, v3
	v_mov_b32_e32 v0, 0x3400
	s_nop 3
	s_mul_i32 s10, s10, 24
	s_mul_i32 s11, s11, 24
	s_waitcnt vmcnt(0)
	v_readfirstlane_b32 s12, v4
	s_nop 3
	s_add_u32 s12, s12, 1
	s_cmp_lg_u32 s12, s10
	s_cbranch_scc1 .Lgb30_poll
	buffer_wbl2 sc1
	s_waitcnt vmcnt(0)
	global_atomic_add v0, v1, s[84:85]

.Lgb30_wait:
	s_barrier
.LBB0_2845:
	s_cmp_gt_i32 s60, 31
	s_cselect_b64 s[2:3], -1, 0
	s_cmp_lt_i32 s61, 31
	s_cselect_b64 s[4:5], -1, 0
	s_or_b64 s[2:3], s[2:3], s[4:5]
	s_and_b64 vcc, exec, s[2:3]
	s_cbranch_vccnz .LBB0_2909
	s_load_dwordx2 s[4:5], s[0:1], 0xe0
	s_load_dword s16, s[0:1], 0xf0
	v_and_b32_e32 v240, 63, v162
	v_lshrrev_b32_e32 v247, 6, v162
	v_lshrrev_b32_e32 v242, 3, v240
	v_lshl_add_u32 v242, v247, 5, v242
	v_and_b32_e32 v243, 7, v240
	v_lshrrev_b32_e32 v244, 4, v240
	v_xor_b32_e32 v243, v243, v244
	v_lshlrev_b32_e32 v243, 4, v243
	v_mov_b32_e32 v241, 0x800
	v_mad_u32_u24 v248, v242, v241, v243
	v_xor_b32_e32 v249, 64, v248
	v_add_u32_e32 v249, 0x4000, v249
	v_add_u32_e32 v250, 0x8000, v248
	v_xor_b32_e32 v251, 64, v248
	v_add_u32_e32 v251, 0xc000, v251
	v_and_b32_e32 v241, 15, v240
	v_lshrrev_b32_e32 v242, 1, v241
	v_xor_b32_e32 v242, v242, v244
	v_lshlrev_b32_e32 v242, 4, v242
	v_lshl_or_b32 v242, v241, 7, v242
	v_lshrrev_b32_e32 v243, 1, v247
	v_lshl_or_b32 v252, v243, 13, v242
	v_xor_b32_e32 v253, 64, v252
	v_and_b32_e32 v243, 1, v247
	v_lshl_or_b32 v254, v243, 13, v242
	v_xor_b32_e32 v255, 64, v254
	v_and_b32_e32 v240, 63, v162
	v_and_b32_e32 v241, 15, v240
	v_lshrrev_b32_e32 v242, 4, v240
	v_mul_u32_u24_e32 v245, 0x1400, v247
	v_mul_u32_u24_e32 v243, 80, v241
	v_add_u32_e32 v243, v243, v245
	v_lshl_add_u32 v244, v242, 3, v243
	v_lshrrev_b32_e32 v243, 2, v240
	v_mul_u32_u24_e32 v246, 80, v243
	v_add_u32_e32 v246, v246, v245
	v_and_b32_e32 v241, 3, v240
	v_lshl_add_u32 v246, v241, 4, v246
	v_mov_b32_e32 v245, v244
	v_lshrrev_b32_e32 v242, 1, v247
	v_lshl_add_u32 v243, v242, 6, v243
	v_mov_b32_e32 v242, 0x1600
	v_mul_u32_u24_e32 v243, v243, v242
	v_and_b32_e32 v242, 1, v247
	v_lshl_add_u32 v243, v242, 6, v243
	v_lshl_add_u32 v239, v241, 4, v243
	s_waitcnt lgkmcnt(0)
	s_add_u32 s26, s4, 0x8b7a100
	s_addc_u32 s27, s5, 0
	s_add_u32 s28, s4, 0x4580000
	s_addc_u32 s29, s5, 0
	s_mov_b32 s15, s58

.Lf31_end:
.LBB0_2855:
	s_cmp_lt_i32 s61, 32
	s_cbranch_scc1 .LBB0_2909
	s_waitcnt vmcnt(0) lgkmcnt(0)
	s_barrier
	v_readfirstlane_b32 s2, v162
	s_lshl_b32 s3, s33, 8
	s_add_u32 s6, s84, s3
	s_addc_u32 s7, s85, 0
	s_cmp_lg_u32 s2, 0
	s_cbranch_scc1 .Lgb31_wait
	s_mov_b64 s[8:9], exec
	s_mov_b64 exec, 1
	v_mov_b32_e32 v0, 0x12000
	ds_read_b64 v[2:3], v0
	v_mov_b32_e32 v0, 0x1400
	v_mov_b32_e32 v1, 1
	global_atomic_add v4, v0, v1, s[6:7] sc0
	s_mov_b32 s13, 0
	s_waitcnt lgkmcnt(0)
	v_readfirstlane_b32 s10, v2
	v_readfirstlane_b32 s11, v3
	v_mov_b32_e32 v0, 0x3400
	s_nop 3
	s_mul_i32 s10, s10, 25
	s_mul_i32 s11, s11, 25
	s_waitcnt vmcnt(0)
	v_readfirstlane_b32 s12, v4
	s_nop 3
	s_add_u32 s12, s12, 1
	s_cmp_lg_u32 s12, s10
	s_cbranch_scc1 .Lgb31_poll
	buffer_wbl2 sc1
	s_waitcnt vmcnt(0)
	global_atomic_add v0, v1, s[84:85]

.Lgb31_wait:
	s_barrier
.LBB0_2909:
	s_cmp_gt_i32 s60, 32
	s_cselect_b64 s[2:3], -1, 0
	s_cmp_lt_i32 s61, 32
	s_cselect_b64 s[4:5], -1, 0
	s_or_b64 s[2:3], s[2:3], s[4:5]
	s_and_b64 vcc, exec, s[2:3]
	s_cbranch_vccnz .LBB0_2969
	s_load_dwordx2 s[4:5], s[0:1], 0xe0
	s_load_dword s16, s[0:1], 0xf0
	v_and_b32_e32 v240, 63, v162
	v_lshrrev_b32_e32 v247, 6, v162
	v_lshrrev_b32_e32 v242, 3, v240
	v_lshl_add_u32 v242, v247, 5, v242
	v_and_b32_e32 v243, 7, v240
	v_lshrrev_b32_e32 v244, 4, v240
	v_xor_b32_e32 v243, v243, v244
	v_lshlrev_b32_e32 v243, 4, v243
	v_mov_b32_e32 v241, 0x1600
	v_mad_u32_u24 v248, v242, v241, v243
	v_xor_b32_e32 v249, 64, v248
	v_add_u32_e32 v249, 0xb000, v249
	v_add_u32_e32 v250, 0x16000, v248
	v_xor_b32_e32 v251, 64, v248
	v_add_u32_e32 v251, 0x21000, v251
	v_and_b32_e32 v241, 15, v240
	v_lshrrev_b32_e32 v242, 1, v241
	v_xor_b32_e32 v242, v242, v244
	v_lshlrev_b32_e32 v242, 4, v242
	v_lshl_or_b32 v242, v241, 7, v242
	v_lshrrev_b32_e32 v243, 1, v247
	v_lshl_or_b32 v252, v243, 13, v242
	v_xor_b32_e32 v253, 64, v252
	v_and_b32_e32 v243, 1, v247
	v_lshl_or_b32 v254, v243, 13, v242
	v_xor_b32_e32 v255, 64, v254
	v_and_b32_e32 v240, 63, v162
	v_and_b32_e32 v241, 15, v240
	v_lshrrev_b32_e32 v242, 4, v240
	v_lshrrev_b32_e32 v243, 1, v247
	v_and_b32_e32 v244, 1, v247
	v_lshl_or_b32 v245, v244, 6, v241
	v_lshlrev_b32_e32 v243, 4, v243
	v_add_u32_e32 v243, v243, v242
	v_lshl_add_u32 v246, v243, 12, v245
	v_lshlrev_b32_e32 v246, 2, v246
	v_lshlrev_b32_e32 v245, 2, v245
	s_waitcnt lgkmcnt(0)
	s_add_u32 s26, s4, 0x9b7a100
	s_addc_u32 s27, s5, 0
	s_add_u32 s28, s4, 0x6100000
	s_addc_u32 s29, s5, 0
	s_mov_b32 s15, s58
